# v55 plus the 16 pre-barrier vmcnt(8) and lgkmcnt(0) wait pairs in the GEMM K-loops merged into single s_waitcnt instructions
# baseline (speedup 1.0000x reference)
; #define PG8_STAGE(bufoff, gbase, voff) do { _Pragma("unroll") for (int _i = 0; _i < 2; ++_i) \
;         __builtin_amdgcn_global_load_lds((const unsigned*)((const char*)(gbase) + (voff)[_i]), (PG8_LAS unsigned*)(lds + (bufoff) + ldsw + _i * 8192), 16, 0, 0); } while (0)
; #define PG8_LDA(dst, b, h) do { _Pragma("unroll") for (int m = 0; m < 4; ++m) _Pragma("unroll") for (int k = 0; k < 2; ++k) dst[m][k] = *(const PG8_LAS bf16x8*)(lds + PG8_SA(b, h) + aoff + m * 2048 + k * 1024); } while (0)
; #define PG8_LDB(dst, b, h) do { _Pragma("unroll") for (int n = 0; n < 2; ++n) _Pragma("unroll") for (int k = 0; k < 2; ++k) dst[n][k] = *(const PG8_LAS bf16x8*)(lds + PG8_SB(b, h) + boff + n * 2048 + k * 1024); } while (0)
; #define PG8_MMA(ai, bj, At, Bt) do { __builtin_amdgcn_s_setprio(1); _Pragma("unroll") for (int m = 0; m < 4; ++m) _Pragma("unroll") for (int n = 0; n < 2; ++n) _Pragma("unroll") for (int k = 0; k < 2; ++k) \
;         acc[ai][bj][m][n] = __builtin_amdgcn_mfma_f32_16x16x32_bf16(Bt[n][k], At[m][k], acc[ai][bj][m][n], 0, 0, 0); __builtin_amdgcn_s_setprio(0); } while (0)
; #define PG8_WAIT_V(n) asm volatile("s_waitcnt vmcnt(" #n ")" ::: "memory")
; #define PG8_WAIT_L(n) asm volatile("s_waitcnt lgkmcnt(" #n ")" ::: "memory")
; template <class Epi, class Sched, bool ALIGN_EPI = false, bool SP2 = false>
; __device__ __forceinline__ void gemm_phase(PG8_LAS unsigned char* lds, const Gemm g, const Sched& S, const Epi& E) {
;     ...
;             const bool last = (t == unt - 2);
;             const char* a1 = cA + (size_t)(t + 1) * kstep;
;             const char* a2 = last ? nA : cA + (size_t)(t + 2) * kstep; const char* b2 = last ? nB : cB + (size_t)(t + 2) * kstep;
;             const char* a3 = a2 + kstep; const char* b3 = b2 + kstep;
;             if (last && has_next) S.a_ready(nxt);
;             if constexpr (SP2) {
;             PG8_LDB(B0, 0, 0); PG8_LDB(B1, 0, 1); PG8_SCHED; PG8_LDA(At, 0, 0); PG8_STAGE(PG8_SA(1, 1), a1 + hstep, voffA);
;             PG8_WAIT_V(8); PG8_WAIT_L(0); PG8_BAR; PG8_MMA(0, 0, At, B0); PG8_MMA(0, 1, At, B1); PG8_BAR; PG8_SCHED;
;             PG8_LDA(At, 0, 1); PG8_STAGE(PG8_SB(0, 0), b2, voffB); PG8_STAGE(PG8_SB(0, 1), b2 + hstep, voffB); PG8_STAGE(PG8_SA(0, 0), a2, voffA);
;             PG8_WAIT_V(8); PG8_WAIT_L(0); PG8_BAR; PG8_MMA(1, 0, At, B0); PG8_MMA(1, 1, At, B1); PG8_BAR; PG8_SCHED;
.LBB0_197:
	s_add_u32 s6, s46, 0xfffc0080
	s_addc_u32 s7, s47, -1
	s_add_i32 s71, 0, 0x10000
	s_cmp_eq_u32 s70, 12
	s_cselect_b32 s51, s35, s7
	s_cselect_b32 s50, s66, s6
	s_cselect_b32 s49, s31, s69
	s_cselect_b32 s48, s67, s68
	s_add_i32 s6, 0, 0x14000
	v_add_u32_e32 v156, s71, v145
	v_add_u32_e32 v172, s6, v145
	ds_read_b128 v[140:143], v156
	ds_read_b128 v[148:151], v156 offset:1024
	ds_read_b128 v[152:155], v156 offset:2048
	ds_read_b128 v[156:159], v156 offset:3072
	ds_read_b128 v[160:163], v172
	ds_read_b128 v[164:167], v172 offset:1024
	ds_read_b128 v[168:171], v172 offset:2048
	ds_read_b128 v[172:175], v172 offset:3072
	s_add_i32 m0, s45, 0xc000
	ds_read_b128 v[176:179], v147
	ds_read_b128 v[180:183], v147 offset:1024
	ds_read_b128 v[184:187], v147 offset:2048
	ds_read_b128 v[188:191], v147 offset:3072
	ds_read_b128 v[192:195], v147 offset:4096
	ds_read_b128 v[196:199], v147 offset:5120
	ds_read_b128 v[200:203], v147 offset:6144
	ds_read_b128 v[212:215], v147 offset:7168
	global_load_lds_dwordx4 v136, s[46:47]
	s_add_i32 m0, s45, 0xe000
	s_nop 0
	global_load_lds_dwordx4 v138, s[46:47]
	s_waitcnt vmcnt(8) lgkmcnt(0)
	s_barrier
	s_setprio 1
	v_mfma_f32_16x16x32_bf16 v[126:129], v[140:143], v[176:179], v[126:129]
	v_mfma_f32_16x16x32_bf16 v[122:125], v[152:155], v[176:179], v[122:125]
	v_mfma_f32_16x16x32_bf16 v[118:121], v[140:143], v[184:187], v[118:121]
	v_mfma_f32_16x16x32_bf16 v[110:113], v[152:155], v[184:187], v[110:113]
	v_mfma_f32_16x16x32_bf16 v[102:105], v[140:143], v[192:195], v[102:105]
	v_mfma_f32_16x16x32_bf16 v[94:97], v[152:155], v[192:195], v[94:97]
	v_mfma_f32_16x16x32_bf16 v[86:89], v[140:143], v[200:203], v[86:89]
	v_mfma_f32_16x16x32_bf16 v[78:81], v[152:155], v[200:203], v[78:81]
	v_mfma_f32_16x16x32_bf16 v[126:129], v[148:151], v[180:183], v[126:129]
	v_mfma_f32_16x16x32_bf16 v[122:125], v[156:159], v[180:183], v[122:125]
	v_mfma_f32_16x16x32_bf16 v[118:121], v[148:151], v[188:191], v[118:121]
	v_mfma_f32_16x16x32_bf16 v[110:113], v[156:159], v[188:191], v[110:113]
	v_mfma_f32_16x16x32_bf16 v[102:105], v[148:151], v[196:199], v[102:105]
	v_mfma_f32_16x16x32_bf16 v[94:97], v[156:159], v[196:199], v[94:97]
	v_mfma_f32_16x16x32_bf16 v[86:89], v[148:151], v[212:215], v[86:89]
	v_mfma_f32_16x16x32_bf16 v[78:81], v[156:159], v[212:215], v[78:81]
	v_mfma_f32_16x16x32_bf16 v[114:117], v[160:163], v[176:179], v[114:117]
	v_mfma_f32_16x16x32_bf16 v[106:109], v[168:171], v[176:179], v[106:109]
	v_mfma_f32_16x16x32_bf16 v[98:101], v[160:163], v[184:187], v[98:101]
	v_mfma_f32_16x16x32_bf16 v[90:93], v[168:171], v[184:187], v[90:93]
	v_mfma_f32_16x16x32_bf16 v[82:85], v[160:163], v[192:195], v[82:85]
	v_mfma_f32_16x16x32_bf16 v[74:77], v[168:171], v[192:195], v[74:77]
	v_mfma_f32_16x16x32_bf16 v[70:73], v[160:163], v[200:203], v[70:73]
	v_mfma_f32_16x16x32_bf16 v[66:69], v[168:171], v[200:203], v[66:69]
	v_mfma_f32_16x16x32_bf16 v[114:117], v[164:167], v[180:183], v[114:117]
	v_mfma_f32_16x16x32_bf16 v[106:109], v[172:175], v[180:183], v[106:109]
	v_mfma_f32_16x16x32_bf16 v[98:101], v[164:167], v[188:191], v[98:101]
	v_mfma_f32_16x16x32_bf16 v[90:93], v[172:175], v[188:191], v[90:93]
	v_mfma_f32_16x16x32_bf16 v[82:85], v[164:167], v[196:199], v[82:85]
	v_mfma_f32_16x16x32_bf16 v[74:77], v[172:175], v[196:199], v[74:77]
	v_mfma_f32_16x16x32_bf16 v[70:73], v[164:167], v[212:215], v[70:73]
	v_mfma_f32_16x16x32_bf16 v[66:69], v[172:175], v[212:215], v[66:69]
	s_setprio 0
	s_barrier
	s_add_i32 s7, s71, s60
	s_add_u32 s98, s48, s22
	s_addc_u32 s99, s49, s23
	s_mov_b32 m0, s7
	ds_read_b128 v[176:179], v147 offset:16384
	ds_read_b128 v[180:183], v147 offset:17408
	ds_read_b128 v[184:187], v147 offset:18432
	ds_read_b128 v[188:191], v147 offset:19456
	ds_read_b128 v[192:195], v147 offset:20480
	ds_read_b128 v[196:199], v147 offset:21504
	ds_read_b128 v[200:203], v147 offset:22528
	ds_read_b128 v[212:215], v147 offset:23552
	global_load_lds_dwordx4 v0, s[48:49]
	s_add_i32 m0, s7, 0x2000
	s_add_u32 s76, s48, 0x40000
	s_addc_u32 s77, s49, 0
	s_add_i32 s6, s6, s60
	global_load_lds_dwordx4 v134, s[48:49]
	s_mov_b32 m0, s6
	s_add_u32 s100, s50, s22
	s_addc_u32 s101, s51, s23
	global_load_lds_dwordx4 v0, s[76:77]
	s_add_i32 m0, s6, 0x2000
	s_nop 0
	global_load_lds_dwordx4 v134, s[76:77]
	s_mov_b32 m0, s45
	s_nop 0
	global_load_lds_dwordx4 v130, s[50:51]
	s_mov_b32 m0, s4
	s_nop 0
	global_load_lds_dwordx4 v132, s[50:51]
	s_waitcnt vmcnt(8) lgkmcnt(0)
	s_barrier
	s_setprio 1
	v_mfma_f32_16x16x32_bf16 v[62:65], v[140:143], v[176:179], v[62:65]
	v_mfma_f32_16x16x32_bf16 v[58:61], v[152:155], v[176:179], v[58:61]
	v_mfma_f32_16x16x32_bf16 v[54:57], v[140:143], v[184:187], v[54:57]
	v_mfma_f32_16x16x32_bf16 v[46:49], v[152:155], v[184:187], v[46:49]
	v_mfma_f32_16x16x32_bf16 v[38:41], v[140:143], v[192:195], v[38:41]
	v_mfma_f32_16x16x32_bf16 v[30:33], v[152:155], v[192:195], v[30:33]
	v_mfma_f32_16x16x32_bf16 v[22:25], v[140:143], v[200:203], v[22:25]
	v_mfma_f32_16x16x32_bf16 v[14:17], v[152:155], v[200:203], v[14:17]
	v_mfma_f32_16x16x32_bf16 v[62:65], v[148:151], v[180:183], v[62:65]
	v_mfma_f32_16x16x32_bf16 v[58:61], v[156:159], v[180:183], v[58:61]
	v_mfma_f32_16x16x32_bf16 v[54:57], v[148:151], v[188:191], v[54:57]
	v_mfma_f32_16x16x32_bf16 v[46:49], v[156:159], v[188:191], v[46:49]
	v_mfma_f32_16x16x32_bf16 v[38:41], v[148:151], v[196:199], v[38:41]
	v_mfma_f32_16x16x32_bf16 v[30:33], v[156:159], v[196:199], v[30:33]
	v_mfma_f32_16x16x32_bf16 v[22:25], v[148:151], v[212:215], v[22:25]
	v_mfma_f32_16x16x32_bf16 v[14:17], v[156:159], v[212:215], v[14:17]
	v_mfma_f32_16x16x32_bf16 v[50:53], v[160:163], v[176:179], v[50:53]
	v_mfma_f32_16x16x32_bf16 v[42:45], v[168:171], v[176:179], v[42:45]
	v_mfma_f32_16x16x32_bf16 v[34:37], v[160:163], v[184:187], v[34:37]
	v_mfma_f32_16x16x32_bf16 v[26:29], v[168:171], v[184:187], v[26:29]
	v_mfma_f32_16x16x32_bf16 v[18:21], v[160:163], v[192:195], v[18:21]
	v_mfma_f32_16x16x32_bf16 v[10:13], v[168:171], v[192:195], v[10:13]
	v_mfma_f32_16x16x32_bf16 v[6:9], v[160:163], v[200:203], v[6:9]
	v_mfma_f32_16x16x32_bf16 v[2:5], v[168:171], v[200:203], v[2:5]
	v_mfma_f32_16x16x32_bf16 v[50:53], v[164:167], v[180:183], v[50:53]
	v_mfma_f32_16x16x32_bf16 v[42:45], v[172:175], v[180:183], v[42:45]
	v_mfma_f32_16x16x32_bf16 v[34:37], v[164:167], v[188:191], v[34:37]
	v_mfma_f32_16x16x32_bf16 v[26:29], v[172:175], v[188:191], v[26:29]
	v_mfma_f32_16x16x32_bf16 v[18:21], v[164:167], v[196:199], v[18:21]
	v_mfma_f32_16x16x32_bf16 v[10:13], v[172:175], v[196:199], v[10:13]
	v_mfma_f32_16x16x32_bf16 v[6:9], v[164:167], v[212:215], v[6:9]
	v_mfma_f32_16x16x32_bf16 v[2:5], v[172:175], v[212:215], v[2:5]
	s_setprio 0
	s_barrier
; #define PG8_STAGE(bufoff, gbase, voff) do { _Pragma("unroll") for (int _i = 0; _i < 2; ++_i) \
;         __builtin_amdgcn_global_load_lds((const unsigned*)((const char*)(gbase) + (voff)[_i]), (PG8_LAS unsigned*)(lds + (bufoff) + ldsw + _i * 8192), 16, 0, 0); } while (0)
; #define PG8_LDA(dst, b, h) do { _Pragma("unroll") for (int m = 0; m < 4; ++m) _Pragma("unroll") for (int k = 0; k < 2; ++k) dst[m][k] = *(const PG8_LAS bf16x8*)(lds + PG8_SA(b, h) + aoff + m * 2048 + k * 1024); } while (0)
; #define PG8_LDB(dst, b, h) do { _Pragma("unroll") for (int n = 0; n < 2; ++n) _Pragma("unroll") for (int k = 0; k < 2; ++k) dst[n][k] = *(const PG8_LAS bf16x8*)(lds + PG8_SB(b, h) + boff + n * 2048 + k * 1024); } while (0)
; #define PG8_MMA(ai, bj, At, Bt) do { __builtin_amdgcn_s_setprio(1); _Pragma("unroll") for (int m = 0; m < 4; ++m) _Pragma("unroll") for (int n = 0; n < 2; ++n) _Pragma("unroll") for (int k = 0; k < 2; ++k) \
;         acc[ai][bj][m][n] = __builtin_amdgcn_mfma_f32_16x16x32_bf16(Bt[n][k], At[m][k], acc[ai][bj][m][n], 0, 0, 0); __builtin_amdgcn_s_setprio(0); } while (0)
; #define PG8_WAIT_V(n) asm volatile("s_waitcnt vmcnt(" #n ")" ::: "memory")
; #define PG8_WAIT_L(n) asm volatile("s_waitcnt lgkmcnt(" #n ")" ::: "memory")
; #define PG8_BAR __builtin_amdgcn_s_barrier()
; #define PG8_SCHED __builtin_amdgcn_sched_barrier(0)
; template <class Epi, class Sched, bool ALIGN_EPI = false, bool SP2 = false>
; __device__ __forceinline__ void gemm_phase(PG8_LAS unsigned char* lds, const Gemm g, const Sched& S, const Epi& E) {
;     ...
;             PG8_LDB(B0, 1, 0); PG8_LDB(B1, 1, 1); PG8_SCHED; PG8_LDA(At, 1, 0); PG8_STAGE(PG8_SA(0, 1), a2 + hstep, voffA);
;             PG8_WAIT_V(8); PG8_WAIT_L(0); PG8_BAR; PG8_MMA(0, 0, At, B0); PG8_MMA(0, 1, At, B1); PG8_BAR; PG8_SCHED;
;             PG8_LDA(At, 1, 1); PG8_STAGE(PG8_SB(1, 0), b3, voffB); PG8_STAGE(PG8_SB(1, 1), b3 + hstep, voffB); PG8_STAGE(PG8_SA(1, 0), a3, voffA);
;             PG8_WAIT_V(8); PG8_WAIT_L(0); PG8_BAR; PG8_MMA(1, 0, At, B0); PG8_MMA(1, 1, At, B1); PG8_BAR; PG8_SCHED;
;     ...
;         if constexpr (ALIGN_EPI) { if (wr == 0) PG8_BAR; }
	s_add_i32 s6, 0, 0x18000
	s_add_i32 s7, 0, 0x1c000
	v_add_u32_e32 v156, s6, v145
	v_add_u32_e32 v172, s7, v145
	ds_read_b128 v[140:143], v156
	ds_read_b128 v[148:151], v156 offset:1024
	ds_read_b128 v[152:155], v156 offset:2048
	ds_read_b128 v[156:159], v156 offset:3072
	ds_read_b128 v[160:163], v172
	ds_read_b128 v[164:167], v172 offset:1024
	ds_read_b128 v[168:171], v172 offset:2048
	ds_read_b128 v[172:175], v172 offset:3072
	s_add_u32 s50, s50, 0x40000
	s_addc_u32 s51, s51, 0
	s_mov_b32 m0, s5
	ds_read_b128 v[176:179], v147 offset:32768
	ds_read_b128 v[180:183], v147 offset:33792
	ds_read_b128 v[184:187], v147 offset:34816
	ds_read_b128 v[188:191], v147 offset:35840
	ds_read_b128 v[192:195], v147 offset:36864
	ds_read_b128 v[196:199], v147 offset:37888
	ds_read_b128 v[200:203], v147 offset:38912
	ds_read_b128 v[212:215], v147 offset:39936
	global_load_lds_dwordx4 v130, s[50:51]
	s_mov_b32 m0, s61
	s_nop 0
	global_load_lds_dwordx4 v132, s[50:51]
	s_waitcnt vmcnt(8) lgkmcnt(0)
	s_barrier
	s_setprio 1
	v_mfma_f32_16x16x32_bf16 v[126:129], v[140:143], v[176:179], v[126:129]
	v_mfma_f32_16x16x32_bf16 v[122:125], v[152:155], v[176:179], v[122:125]
	v_mfma_f32_16x16x32_bf16 v[118:121], v[140:143], v[184:187], v[118:121]
	v_mfma_f32_16x16x32_bf16 v[110:113], v[152:155], v[184:187], v[110:113]
	v_mfma_f32_16x16x32_bf16 v[102:105], v[140:143], v[192:195], v[102:105]
	v_mfma_f32_16x16x32_bf16 v[94:97], v[152:155], v[192:195], v[94:97]
	v_mfma_f32_16x16x32_bf16 v[86:89], v[140:143], v[200:203], v[86:89]
	v_mfma_f32_16x16x32_bf16 v[78:81], v[152:155], v[200:203], v[78:81]
	v_mfma_f32_16x16x32_bf16 v[126:129], v[148:151], v[180:183], v[126:129]
	v_mfma_f32_16x16x32_bf16 v[122:125], v[156:159], v[180:183], v[122:125]
	v_mfma_f32_16x16x32_bf16 v[118:121], v[148:151], v[188:191], v[118:121]
	v_mfma_f32_16x16x32_bf16 v[110:113], v[156:159], v[188:191], v[110:113]
	v_mfma_f32_16x16x32_bf16 v[102:105], v[148:151], v[196:199], v[102:105]
	v_mfma_f32_16x16x32_bf16 v[94:97], v[156:159], v[196:199], v[94:97]
	v_mfma_f32_16x16x32_bf16 v[86:89], v[148:151], v[212:215], v[86:89]
	v_mfma_f32_16x16x32_bf16 v[78:81], v[156:159], v[212:215], v[78:81]
	v_mfma_f32_16x16x32_bf16 v[114:117], v[160:163], v[176:179], v[114:117]
	v_mfma_f32_16x16x32_bf16 v[106:109], v[168:171], v[176:179], v[106:109]
	v_mfma_f32_16x16x32_bf16 v[98:101], v[160:163], v[184:187], v[98:101]
	v_mfma_f32_16x16x32_bf16 v[90:93], v[168:171], v[184:187], v[90:93]
	v_mfma_f32_16x16x32_bf16 v[82:85], v[160:163], v[192:195], v[82:85]
	v_mfma_f32_16x16x32_bf16 v[74:77], v[168:171], v[192:195], v[74:77]
	v_mfma_f32_16x16x32_bf16 v[70:73], v[160:163], v[200:203], v[70:73]
	v_mfma_f32_16x16x32_bf16 v[66:69], v[168:171], v[200:203], v[66:69]
	v_mfma_f32_16x16x32_bf16 v[114:117], v[164:167], v[180:183], v[114:117]
	v_mfma_f32_16x16x32_bf16 v[106:109], v[172:175], v[180:183], v[106:109]
	v_mfma_f32_16x16x32_bf16 v[98:101], v[164:167], v[188:191], v[98:101]
	v_mfma_f32_16x16x32_bf16 v[90:93], v[172:175], v[188:191], v[90:93]
	v_mfma_f32_16x16x32_bf16 v[82:85], v[164:167], v[196:199], v[82:85]
	v_mfma_f32_16x16x32_bf16 v[74:77], v[172:175], v[196:199], v[74:77]
	v_mfma_f32_16x16x32_bf16 v[70:73], v[164:167], v[212:215], v[70:73]
	v_mfma_f32_16x16x32_bf16 v[66:69], v[172:175], v[212:215], v[66:69]
	s_setprio 0
	s_barrier
	s_add_i32 s6, s6, s60
	s_mov_b32 m0, s6
	ds_read_b128 v[176:179], v147 offset:49152
	ds_read_b128 v[180:183], v147 offset:50176
	ds_read_b128 v[184:187], v147 offset:51200
	ds_read_b128 v[188:191], v147 offset:52224
	ds_read_b128 v[192:195], v147 offset:53248
	ds_read_b128 v[196:199], v147 offset:54272
	ds_read_b128 v[200:203], v147 offset:55296
	ds_read_b128 v[212:215], v147 offset:56320
	global_load_lds_dwordx4 v0, s[98:99]
	s_add_i32 m0, s6, 0x2000
	s_add_u32 s48, s48, 0x40080
	s_addc_u32 s49, s49, 0
	s_add_i32 s6, s7, s60
	global_load_lds_dwordx4 v134, s[98:99]
	s_mov_b32 m0, s6
	s_nop 0
	global_load_lds_dwordx4 v0, s[48:49]
	s_add_i32 m0, s6, 0x2000
	s_nop 0
	global_load_lds_dwordx4 v134, s[48:49]
	s_mov_b32 m0, s62
	s_nop 0
	global_load_lds_dwordx4 v130, s[100:101]
	s_mov_b32 m0, s63
	s_nop 0
	global_load_lds_dwordx4 v132, s[100:101]
	s_waitcnt vmcnt(8) lgkmcnt(0)
	s_barrier
	s_setprio 1
	v_mfma_f32_16x16x32_bf16 v[62:65], v[140:143], v[176:179], v[62:65]
	v_mfma_f32_16x16x32_bf16 v[58:61], v[152:155], v[176:179], v[58:61]
	v_mfma_f32_16x16x32_bf16 v[54:57], v[140:143], v[184:187], v[54:57]
	v_mfma_f32_16x16x32_bf16 v[46:49], v[152:155], v[184:187], v[46:49]
	v_mfma_f32_16x16x32_bf16 v[38:41], v[140:143], v[192:195], v[38:41]
	v_mfma_f32_16x16x32_bf16 v[30:33], v[152:155], v[192:195], v[30:33]
	v_mfma_f32_16x16x32_bf16 v[22:25], v[140:143], v[200:203], v[22:25]
	v_mfma_f32_16x16x32_bf16 v[14:17], v[152:155], v[200:203], v[14:17]
	v_mfma_f32_16x16x32_bf16 v[62:65], v[148:151], v[180:183], v[62:65]
	v_mfma_f32_16x16x32_bf16 v[58:61], v[156:159], v[180:183], v[58:61]
	v_mfma_f32_16x16x32_bf16 v[54:57], v[148:151], v[188:191], v[54:57]
	v_mfma_f32_16x16x32_bf16 v[46:49], v[156:159], v[188:191], v[46:49]
	v_mfma_f32_16x16x32_bf16 v[38:41], v[148:151], v[196:199], v[38:41]
	v_mfma_f32_16x16x32_bf16 v[30:33], v[156:159], v[196:199], v[30:33]
	v_mfma_f32_16x16x32_bf16 v[22:25], v[148:151], v[212:215], v[22:25]
	v_mfma_f32_16x16x32_bf16 v[14:17], v[156:159], v[212:215], v[14:17]
	v_mfma_f32_16x16x32_bf16 v[50:53], v[160:163], v[176:179], v[50:53]
	v_mfma_f32_16x16x32_bf16 v[42:45], v[168:171], v[176:179], v[42:45]
	v_mfma_f32_16x16x32_bf16 v[34:37], v[160:163], v[184:187], v[34:37]
	v_mfma_f32_16x16x32_bf16 v[26:29], v[168:171], v[184:187], v[26:29]
	v_mfma_f32_16x16x32_bf16 v[18:21], v[160:163], v[192:195], v[18:21]
	v_mfma_f32_16x16x32_bf16 v[10:13], v[168:171], v[192:195], v[10:13]
	v_mfma_f32_16x16x32_bf16 v[6:9], v[160:163], v[200:203], v[6:9]
	v_mfma_f32_16x16x32_bf16 v[2:5], v[168:171], v[200:203], v[2:5]
	v_mfma_f32_16x16x32_bf16 v[50:53], v[164:167], v[180:183], v[50:53]
	v_mfma_f32_16x16x32_bf16 v[42:45], v[172:175], v[180:183], v[42:45]
	v_mfma_f32_16x16x32_bf16 v[34:37], v[164:167], v[188:191], v[34:37]
	v_mfma_f32_16x16x32_bf16 v[26:29], v[172:175], v[188:191], v[26:29]
	v_mfma_f32_16x16x32_bf16 v[18:21], v[164:167], v[196:199], v[18:21]
	v_mfma_f32_16x16x32_bf16 v[10:13], v[172:175], v[196:199], v[10:13]
	v_mfma_f32_16x16x32_bf16 v[6:9], v[164:167], v[212:215], v[6:9]
	v_mfma_f32_16x16x32_bf16 v[2:5], v[172:175], v[212:215], v[2:5]
	s_setprio 0
	s_barrier
	s_add_i32 s70, s70, 2
	s_add_u32 s46, s46, 0x100
	s_addc_u32 s47, s47, 0
	s_add_u32 s68, s68, 0x100
	s_addc_u32 s69, s69, 0
	s_cmp_gt_u32 s70, 13
	s_cbranch_scc0 .LBB0_197
	s_and_b64 vcc, exec, s[26:27]
	s_cbranch_vccz .LBB0_200
	s_barrier

; #define PG8_STAGE(bufoff, gbase, voff) do { _Pragma("unroll") for (int _i = 0; _i < 2; ++_i) \
;         __builtin_amdgcn_global_load_lds((const unsigned*)((const char*)(gbase) + (voff)[_i]), (PG8_LAS unsigned*)(lds + (bufoff) + ldsw + _i * 8192), 16, 0, 0); } while (0)
; #define PG8_LDA(dst, b, h) do { _Pragma("unroll") for (int m = 0; m < 4; ++m) _Pragma("unroll") for (int k = 0; k < 2; ++k) dst[m][k] = *(const PG8_LAS bf16x8*)(lds + PG8_SA(b, h) + aoff + m * 2048 + k * 1024); } while (0)
; #define PG8_LDB(dst, b, h) do { _Pragma("unroll") for (int n = 0; n < 2; ++n) _Pragma("unroll") for (int k = 0; k < 2; ++k) dst[n][k] = *(const PG8_LAS bf16x8*)(lds + PG8_SB(b, h) + boff + n * 2048 + k * 1024); } while (0)
; #define PG8_MMA(ai, bj, At, Bt) do { __builtin_amdgcn_s_setprio(1); _Pragma("unroll") for (int m = 0; m < 4; ++m) _Pragma("unroll") for (int n = 0; n < 2; ++n) _Pragma("unroll") for (int k = 0; k < 2; ++k) \
;         acc[ai][bj][m][n] = __builtin_amdgcn_mfma_f32_16x16x32_bf16(Bt[n][k], At[m][k], acc[ai][bj][m][n], 0, 0, 0); __builtin_amdgcn_s_setprio(0); } while (0)
; #define PG8_WAIT_V(n) asm volatile("s_waitcnt vmcnt(" #n ")" ::: "memory")
; #define PG8_WAIT_L(n) asm volatile("s_waitcnt lgkmcnt(" #n ")" ::: "memory")
; template <class Epi, class Sched, bool ALIGN_EPI = false, bool SP2 = false>
; __device__ __forceinline__ void gemm_phase(PG8_LAS unsigned char* lds, const Gemm g, const Sched& S, const Epi& E) {
;     ...
;             const bool last = (t == unt - 2);
;             const char* a1 = cA + (size_t)(t + 1) * kstep;
;             const char* a2 = last ? nA : cA + (size_t)(t + 2) * kstep; const char* b2 = last ? nB : cB + (size_t)(t + 2) * kstep;
;             const char* a3 = a2 + kstep; const char* b3 = b2 + kstep;
;             if (last && has_next) S.a_ready(nxt);
;             if constexpr (SP2) {
;             PG8_LDB(B0, 0, 0); PG8_LDB(B1, 0, 1); PG8_SCHED; PG8_LDA(At, 0, 0); PG8_STAGE(PG8_SA(1, 1), a1 + hstep, voffA);
;             PG8_WAIT_V(8); PG8_WAIT_L(0); PG8_BAR; PG8_MMA(0, 0, At, B0); PG8_MMA(0, 1, At, B1); PG8_BAR; PG8_SCHED;
;             PG8_LDA(At, 0, 1); PG8_STAGE(PG8_SB(0, 0), b2, voffB); PG8_STAGE(PG8_SB(0, 1), b2 + hstep, voffB); PG8_STAGE(PG8_SA(0, 0), a2, voffA);
;             PG8_WAIT_V(8); PG8_WAIT_L(0); PG8_BAR; PG8_MMA(1, 0, At, B0); PG8_MMA(1, 1, At, B1); PG8_BAR; PG8_SCHED;
.LBB0_768:
	s_add_i32 s53, s51, 2
	s_add_u32 s40, s34, 0x100
	s_addc_u32 s41, s35, 0
	s_add_i32 s6, 0, 0x10000
	s_cmp_eq_u32 s5, s51
	s_cselect_b32 s63, s57, s41
	s_cselect_b32 s62, s56, s40
	s_cselect_b32 s61, s59, s27
	s_cselect_b32 s60, s58, s25
	s_add_i32 s51, 0, 0x14000
	s_waitcnt vmcnt(0)
	v_add_u32_e32 v78, s6, v163
	v_add_u32_e32 v160, s51, v163
	ds_read_b128 v[54:57], v78
	ds_read_b128 v[62:65], v78 offset:1024
	ds_read_b128 v[70:73], v78 offset:2048
	ds_read_b128 v[78:81], v78 offset:3072
	ds_read_b128 v[152:155], v160
	ds_read_b128 v[156:159], v160 offset:1024
	ds_read_b128 v[166:169], v160 offset:2048
	ds_read_b128 v[170:173], v160 offset:3072
	s_add_i32 m0, s45, 0xc000
	ds_read_b128 v[174:177], v165
	ds_read_b128 v[178:181], v165 offset:1024
	ds_read_b128 v[182:185], v165 offset:2048
	ds_read_b128 v[186:189], v165 offset:3072
	ds_read_b128 v[190:193], v165 offset:4096
	ds_read_b128 v[194:197], v165 offset:5120
	ds_read_b128 v[198:201], v165 offset:6144
	ds_read_b128 v[202:205], v165 offset:7168
	global_load_lds_dwordx4 v148, s[34:35]
	s_add_i32 m0, s45, 0xe000
	s_nop 0
	global_load_lds_dwordx4 v150, s[34:35]
	s_waitcnt vmcnt(8) lgkmcnt(0)
	s_barrier
	s_setprio 1
	v_mfma_f32_16x16x32_bf16 v[142:145], v[54:57], v[174:177], v[142:145]
	v_mfma_f32_16x16x32_bf16 v[138:141], v[70:73], v[174:177], v[138:141]
	v_mfma_f32_16x16x32_bf16 v[126:129], v[54:57], v[182:185], v[126:129]
	v_mfma_f32_16x16x32_bf16 v[122:125], v[70:73], v[182:185], v[122:125]
	v_mfma_f32_16x16x32_bf16 v[110:113], v[54:57], v[190:193], v[110:113]
	v_mfma_f32_16x16x32_bf16 v[106:109], v[70:73], v[190:193], v[106:109]
	v_mfma_f32_16x16x32_bf16 v[94:97], v[54:57], v[198:201], v[94:97]
	v_mfma_f32_16x16x32_bf16 v[90:93], v[70:73], v[198:201], v[90:93]
	v_mfma_f32_16x16x32_bf16 v[142:145], v[62:65], v[178:181], v[142:145]
	v_mfma_f32_16x16x32_bf16 v[138:141], v[78:81], v[178:181], v[138:141]
	v_mfma_f32_16x16x32_bf16 v[126:129], v[62:65], v[186:189], v[126:129]
	v_mfma_f32_16x16x32_bf16 v[122:125], v[78:81], v[186:189], v[122:125]
	v_mfma_f32_16x16x32_bf16 v[110:113], v[62:65], v[194:197], v[110:113]
	v_mfma_f32_16x16x32_bf16 v[106:109], v[78:81], v[194:197], v[106:109]
	v_mfma_f32_16x16x32_bf16 v[94:97], v[62:65], v[202:205], v[94:97]
	v_mfma_f32_16x16x32_bf16 v[90:93], v[78:81], v[202:205], v[90:93]
	v_mfma_f32_16x16x32_bf16 v[134:137], v[152:155], v[174:177], v[134:137]
	v_mfma_f32_16x16x32_bf16 v[130:133], v[166:169], v[174:177], v[130:133]
	v_mfma_f32_16x16x32_bf16 v[118:121], v[152:155], v[182:185], v[118:121]
	v_mfma_f32_16x16x32_bf16 v[114:117], v[166:169], v[182:185], v[114:117]
	v_mfma_f32_16x16x32_bf16 v[102:105], v[152:155], v[190:193], v[102:105]
	v_mfma_f32_16x16x32_bf16 v[98:101], v[166:169], v[190:193], v[98:101]
	v_mfma_f32_16x16x32_bf16 v[86:89], v[152:155], v[198:201], v[86:89]
	v_mfma_f32_16x16x32_bf16 v[82:85], v[166:169], v[198:201], v[82:85]
	v_mfma_f32_16x16x32_bf16 v[134:137], v[156:159], v[178:181], v[134:137]
	v_mfma_f32_16x16x32_bf16 v[130:133], v[170:173], v[178:181], v[130:133]
	v_mfma_f32_16x16x32_bf16 v[118:121], v[156:159], v[186:189], v[118:121]
	v_mfma_f32_16x16x32_bf16 v[114:117], v[170:173], v[186:189], v[114:117]
	v_mfma_f32_16x16x32_bf16 v[102:105], v[156:159], v[194:197], v[102:105]
	v_mfma_f32_16x16x32_bf16 v[98:101], v[170:173], v[194:197], v[98:101]
	v_mfma_f32_16x16x32_bf16 v[86:89], v[156:159], v[202:205], v[86:89]
	v_mfma_f32_16x16x32_bf16 v[82:85], v[170:173], v[202:205], v[82:85]
	s_setprio 0
	s_barrier
	s_add_i32 s6, s6, s69
	s_add_u32 s98, s60, s22
	s_addc_u32 s99, s61, s23
	s_mov_b32 m0, s6
	ds_read_b128 v[174:177], v165 offset:16384
	ds_read_b128 v[178:181], v165 offset:17408
	ds_read_b128 v[182:185], v165 offset:18432
	ds_read_b128 v[186:189], v165 offset:19456
	ds_read_b128 v[190:193], v165 offset:20480
	ds_read_b128 v[194:197], v165 offset:21504
	ds_read_b128 v[198:201], v165 offset:22528
	ds_read_b128 v[202:205], v165 offset:23552
	global_load_lds_dwordx4 v0, s[60:61]
	s_add_i32 m0, s6, 0x2000
	s_add_u32 s6, s60, 0x40000
	s_addc_u32 s7, s61, 0
	s_add_i32 s34, s51, s69
	global_load_lds_dwordx4 v146, s[60:61]
	s_mov_b32 m0, s34
	s_add_u32 s100, s62, s22
	s_addc_u32 s101, s63, s23
	global_load_lds_dwordx4 v0, s[6:7]
	s_add_i32 m0, s34, 0x2000
	s_nop 0
	global_load_lds_dwordx4 v146, s[6:7]
	s_mov_b32 m0, s45
	s_nop 0
	global_load_lds_dwordx4 v0, s[62:63]
	s_mov_b32 m0, s82
	s_nop 0
	global_load_lds_dwordx4 v146, s[62:63]
	s_waitcnt vmcnt(8) lgkmcnt(0)
	s_barrier
	s_setprio 1
	v_mfma_f32_16x16x32_bf16 v[74:77], v[54:57], v[174:177], v[74:77]
	v_mfma_f32_16x16x32_bf16 v[66:69], v[70:73], v[174:177], v[66:69]
	v_mfma_f32_16x16x32_bf16 v[46:49], v[54:57], v[182:185], v[46:49]
	v_mfma_f32_16x16x32_bf16 v[42:45], v[70:73], v[182:185], v[42:45]
	v_mfma_f32_16x16x32_bf16 v[30:33], v[54:57], v[190:193], v[30:33]
	v_mfma_f32_16x16x32_bf16 v[26:29], v[70:73], v[190:193], v[26:29]
	v_mfma_f32_16x16x32_bf16 v[14:17], v[54:57], v[198:201], v[14:17]
	v_mfma_f32_16x16x32_bf16 v[10:13], v[70:73], v[198:201], v[10:13]
	v_mfma_f32_16x16x32_bf16 v[74:77], v[62:65], v[178:181], v[74:77]
	v_mfma_f32_16x16x32_bf16 v[66:69], v[78:81], v[178:181], v[66:69]
	v_mfma_f32_16x16x32_bf16 v[46:49], v[62:65], v[186:189], v[46:49]
	v_mfma_f32_16x16x32_bf16 v[42:45], v[78:81], v[186:189], v[42:45]
	v_mfma_f32_16x16x32_bf16 v[30:33], v[62:65], v[194:197], v[30:33]
	v_mfma_f32_16x16x32_bf16 v[26:29], v[78:81], v[194:197], v[26:29]
	v_mfma_f32_16x16x32_bf16 v[14:17], v[62:65], v[202:205], v[14:17]
	v_mfma_f32_16x16x32_bf16 v[10:13], v[78:81], v[202:205], v[10:13]
	v_mfma_f32_16x16x32_bf16 v[50:53], v[166:169], v[174:177], v[50:53]
	v_mfma_f32_16x16x32_bf16 v[38:41], v[152:155], v[182:185], v[38:41]
	v_mfma_f32_16x16x32_bf16 v[34:37], v[166:169], v[182:185], v[34:37]
	v_mfma_f32_16x16x32_bf16 v[22:25], v[152:155], v[190:193], v[22:25]
	v_mfma_f32_16x16x32_bf16 v[18:21], v[166:169], v[190:193], v[18:21]
	v_mfma_f32_16x16x32_bf16 v[6:9], v[152:155], v[198:201], v[6:9]
	v_mfma_f32_16x16x32_bf16 v[2:5], v[166:169], v[198:201], v[2:5]
	v_mfma_f32_16x16x32_bf16 v[54:57], v[152:155], v[174:177], v[58:61]
	v_mfma_f32_16x16x32_bf16 v[50:53], v[170:173], v[178:181], v[50:53]
	v_mfma_f32_16x16x32_bf16 v[38:41], v[156:159], v[186:189], v[38:41]
	v_mfma_f32_16x16x32_bf16 v[34:37], v[170:173], v[186:189], v[34:37]
	v_mfma_f32_16x16x32_bf16 v[22:25], v[156:159], v[194:197], v[22:25]
	v_mfma_f32_16x16x32_bf16 v[18:21], v[170:173], v[194:197], v[18:21]
	v_mfma_f32_16x16x32_bf16 v[6:9], v[156:159], v[202:205], v[6:9]
	v_mfma_f32_16x16x32_bf16 v[2:5], v[170:173], v[202:205], v[2:5]
	v_mfma_f32_16x16x32_bf16 v[54:57], v[156:159], v[178:181], v[54:57]
	s_setprio 0
	s_barrier
; #define PG8_STAGE(bufoff, gbase, voff) do { _Pragma("unroll") for (int _i = 0; _i < 2; ++_i) \
;         __builtin_amdgcn_global_load_lds((const unsigned*)((const char*)(gbase) + (voff)[_i]), (PG8_LAS unsigned*)(lds + (bufoff) + ldsw + _i * 8192), 16, 0, 0); } while (0)
; #define PG8_LDA(dst, b, h) do { _Pragma("unroll") for (int m = 0; m < 4; ++m) _Pragma("unroll") for (int k = 0; k < 2; ++k) dst[m][k] = *(const PG8_LAS bf16x8*)(lds + PG8_SA(b, h) + aoff + m * 2048 + k * 1024); } while (0)
; #define PG8_LDB(dst, b, h) do { _Pragma("unroll") for (int n = 0; n < 2; ++n) _Pragma("unroll") for (int k = 0; k < 2; ++k) dst[n][k] = *(const PG8_LAS bf16x8*)(lds + PG8_SB(b, h) + boff + n * 2048 + k * 1024); } while (0)
; #define PG8_MMA(ai, bj, At, Bt) do { __builtin_amdgcn_s_setprio(1); _Pragma("unroll") for (int m = 0; m < 4; ++m) _Pragma("unroll") for (int n = 0; n < 2; ++n) _Pragma("unroll") for (int k = 0; k < 2; ++k) \
;         acc[ai][bj][m][n] = __builtin_amdgcn_mfma_f32_16x16x32_bf16(Bt[n][k], At[m][k], acc[ai][bj][m][n], 0, 0, 0); __builtin_amdgcn_s_setprio(0); } while (0)
; #define PG8_WAIT_V(n) asm volatile("s_waitcnt vmcnt(" #n ")" ::: "memory")
; #define PG8_WAIT_L(n) asm volatile("s_waitcnt lgkmcnt(" #n ")" ::: "memory")
; #define PG8_BAR __builtin_amdgcn_s_barrier()
; #define PG8_SCHED __builtin_amdgcn_sched_barrier(0)
; template <class Epi, class Sched, bool ALIGN_EPI = false, bool SP2 = false>
; __device__ __forceinline__ void gemm_phase(PG8_LAS unsigned char* lds, const Gemm g, const Sched& S, const Epi& E) {
;     ...
;             PG8_LDB(B0, 1, 0); PG8_LDB(B1, 1, 1); PG8_SCHED; PG8_LDA(At, 1, 0); PG8_STAGE(PG8_SA(0, 1), a2 + hstep, voffA);
;             PG8_WAIT_V(8); PG8_WAIT_L(0); PG8_BAR; PG8_MMA(0, 0, At, B0); PG8_MMA(0, 1, At, B1); PG8_BAR; PG8_SCHED;
;             PG8_LDA(At, 1, 1); PG8_STAGE(PG8_SB(1, 0), b3, voffB); PG8_STAGE(PG8_SB(1, 1), b3 + hstep, voffB); PG8_STAGE(PG8_SA(1, 0), a3, voffA);
;             PG8_WAIT_V(8); PG8_WAIT_L(0); PG8_BAR; PG8_MMA(1, 0, At, B0); PG8_MMA(1, 1, At, B1); PG8_BAR; PG8_SCHED;
;     ...
;         if constexpr (ALIGN_EPI) { if (wr == 0) PG8_BAR; }
	s_add_i32 s34, 0, 0x18000
	s_add_i32 s35, 0, 0x1c000
	v_add_u32_e32 v78, s34, v163
	v_add_u32_e32 v170, s35, v163
	ds_read_b128 v[58:61], v78
	ds_read_b128 v[62:65], v78 offset:1024
	ds_read_b128 v[70:73], v78 offset:2048
	ds_read_b128 v[78:81], v78 offset:3072
	ds_read_b128 v[152:155], v170
	ds_read_b128 v[156:159], v170 offset:1024
	ds_read_b128 v[166:169], v170 offset:2048
	ds_read_b128 v[170:173], v170 offset:3072
	s_add_u32 s6, s62, 0x40000
	s_addc_u32 s7, s63, 0
	s_mov_b32 m0, s83
	ds_read_b128 v[174:177], v165 offset:32768
	ds_read_b128 v[178:181], v165 offset:33792
	ds_read_b128 v[182:185], v165 offset:34816
	ds_read_b128 v[186:189], v165 offset:35840
	ds_read_b128 v[190:193], v165 offset:36864
	ds_read_b128 v[194:197], v165 offset:37888
	ds_read_b128 v[198:201], v165 offset:38912
	ds_read_b128 v[202:205], v165 offset:39936
	global_load_lds_dwordx4 v0, s[6:7]
	s_mov_b32 m0, s84
	s_nop 0
	global_load_lds_dwordx4 v146, s[6:7]
	s_waitcnt vmcnt(8) lgkmcnt(0)
	s_barrier
	s_setprio 1
	v_mfma_f32_16x16x32_bf16 v[142:145], v[58:61], v[174:177], v[142:145]
	v_mfma_f32_16x16x32_bf16 v[138:141], v[70:73], v[174:177], v[138:141]
	v_mfma_f32_16x16x32_bf16 v[126:129], v[58:61], v[182:185], v[126:129]
	v_mfma_f32_16x16x32_bf16 v[122:125], v[70:73], v[182:185], v[122:125]
	v_mfma_f32_16x16x32_bf16 v[110:113], v[58:61], v[190:193], v[110:113]
	v_mfma_f32_16x16x32_bf16 v[106:109], v[70:73], v[190:193], v[106:109]
	v_mfma_f32_16x16x32_bf16 v[94:97], v[58:61], v[198:201], v[94:97]
	v_mfma_f32_16x16x32_bf16 v[90:93], v[70:73], v[198:201], v[90:93]
	v_mfma_f32_16x16x32_bf16 v[142:145], v[62:65], v[178:181], v[142:145]
	v_mfma_f32_16x16x32_bf16 v[138:141], v[78:81], v[178:181], v[138:141]
	v_mfma_f32_16x16x32_bf16 v[126:129], v[62:65], v[186:189], v[126:129]
	v_mfma_f32_16x16x32_bf16 v[122:125], v[78:81], v[186:189], v[122:125]
	v_mfma_f32_16x16x32_bf16 v[110:113], v[62:65], v[194:197], v[110:113]
	v_mfma_f32_16x16x32_bf16 v[106:109], v[78:81], v[194:197], v[106:109]
	v_mfma_f32_16x16x32_bf16 v[94:97], v[62:65], v[202:205], v[94:97]
	v_mfma_f32_16x16x32_bf16 v[90:93], v[78:81], v[202:205], v[90:93]
	v_mfma_f32_16x16x32_bf16 v[134:137], v[152:155], v[174:177], v[134:137]
	v_mfma_f32_16x16x32_bf16 v[130:133], v[166:169], v[174:177], v[130:133]
	v_mfma_f32_16x16x32_bf16 v[118:121], v[152:155], v[182:185], v[118:121]
	v_mfma_f32_16x16x32_bf16 v[114:117], v[166:169], v[182:185], v[114:117]
	v_mfma_f32_16x16x32_bf16 v[102:105], v[152:155], v[190:193], v[102:105]
	v_mfma_f32_16x16x32_bf16 v[98:101], v[166:169], v[190:193], v[98:101]
	v_mfma_f32_16x16x32_bf16 v[86:89], v[152:155], v[198:201], v[86:89]
	v_mfma_f32_16x16x32_bf16 v[82:85], v[166:169], v[198:201], v[82:85]
	v_mfma_f32_16x16x32_bf16 v[134:137], v[156:159], v[178:181], v[134:137]
	v_mfma_f32_16x16x32_bf16 v[130:133], v[170:173], v[178:181], v[130:133]
	v_mfma_f32_16x16x32_bf16 v[118:121], v[156:159], v[186:189], v[118:121]
	v_mfma_f32_16x16x32_bf16 v[114:117], v[170:173], v[186:189], v[114:117]
	v_mfma_f32_16x16x32_bf16 v[102:105], v[156:159], v[194:197], v[102:105]
	v_mfma_f32_16x16x32_bf16 v[98:101], v[170:173], v[194:197], v[98:101]
	v_mfma_f32_16x16x32_bf16 v[86:89], v[156:159], v[202:205], v[86:89]
	v_mfma_f32_16x16x32_bf16 v[82:85], v[170:173], v[202:205], v[82:85]
	s_setprio 0
	s_barrier
	s_add_i32 s6, s34, s69
	s_mov_b32 m0, s6
	ds_read_b128 v[174:177], v165 offset:49152
	ds_read_b128 v[178:181], v165 offset:50176
	ds_read_b128 v[182:185], v165 offset:51200
	ds_read_b128 v[186:189], v165 offset:52224
	ds_read_b128 v[190:193], v165 offset:53248
	ds_read_b128 v[194:197], v165 offset:54272
	ds_read_b128 v[198:201], v165 offset:55296
	ds_read_b128 v[202:205], v165 offset:56320
	global_load_lds_dwordx4 v0, s[98:99]
	s_add_i32 m0, s6, 0x2000
	s_add_u32 s6, s60, 0x40080
	s_addc_u32 s7, s61, 0
	s_add_i32 s34, s35, s69
	global_load_lds_dwordx4 v146, s[98:99]
	s_mov_b32 m0, s34
	s_nop 0
	global_load_lds_dwordx4 v0, s[6:7]
	s_add_i32 m0, s34, 0x2000
	s_nop 0
	global_load_lds_dwordx4 v146, s[6:7]
	s_mov_b32 m0, s93
	s_nop 0
	global_load_lds_dwordx4 v0, s[100:101]
	s_mov_b32 m0, s94
	s_nop 0
	global_load_lds_dwordx4 v146, s[100:101]
	s_waitcnt vmcnt(8) lgkmcnt(0)
	s_barrier
	s_setprio 1
	v_mfma_f32_16x16x32_bf16 v[74:77], v[58:61], v[174:177], v[74:77]
	v_mfma_f32_16x16x32_bf16 v[66:69], v[70:73], v[174:177], v[66:69]
	v_mfma_f32_16x16x32_bf16 v[46:49], v[58:61], v[182:185], v[46:49]
	v_mfma_f32_16x16x32_bf16 v[42:45], v[70:73], v[182:185], v[42:45]
	v_mfma_f32_16x16x32_bf16 v[30:33], v[58:61], v[190:193], v[30:33]
	v_mfma_f32_16x16x32_bf16 v[26:29], v[70:73], v[190:193], v[26:29]
	v_mfma_f32_16x16x32_bf16 v[14:17], v[58:61], v[198:201], v[14:17]
	v_mfma_f32_16x16x32_bf16 v[10:13], v[70:73], v[198:201], v[10:13]
	v_mfma_f32_16x16x32_bf16 v[74:77], v[62:65], v[178:181], v[74:77]
	v_mfma_f32_16x16x32_bf16 v[66:69], v[78:81], v[178:181], v[66:69]
	v_mfma_f32_16x16x32_bf16 v[46:49], v[62:65], v[186:189], v[46:49]
	v_mfma_f32_16x16x32_bf16 v[42:45], v[78:81], v[186:189], v[42:45]
	v_mfma_f32_16x16x32_bf16 v[30:33], v[62:65], v[194:197], v[30:33]
	v_mfma_f32_16x16x32_bf16 v[26:29], v[78:81], v[194:197], v[26:29]
	v_mfma_f32_16x16x32_bf16 v[14:17], v[62:65], v[202:205], v[14:17]
	v_mfma_f32_16x16x32_bf16 v[10:13], v[78:81], v[202:205], v[10:13]
	v_mfma_f32_16x16x32_bf16 v[54:57], v[152:155], v[174:177], v[54:57]
	v_mfma_f32_16x16x32_bf16 v[50:53], v[166:169], v[174:177], v[50:53]
	v_mfma_f32_16x16x32_bf16 v[38:41], v[152:155], v[182:185], v[38:41]
	v_mfma_f32_16x16x32_bf16 v[34:37], v[166:169], v[182:185], v[34:37]
	v_mfma_f32_16x16x32_bf16 v[22:25], v[152:155], v[190:193], v[22:25]
	v_mfma_f32_16x16x32_bf16 v[18:21], v[166:169], v[190:193], v[18:21]
	v_mfma_f32_16x16x32_bf16 v[6:9], v[152:155], v[198:201], v[6:9]
	v_mfma_f32_16x16x32_bf16 v[2:5], v[166:169], v[198:201], v[2:5]
	v_mfma_f32_16x16x32_bf16 v[58:61], v[156:159], v[178:181], v[54:57]
	v_mfma_f32_16x16x32_bf16 v[50:53], v[170:173], v[178:181], v[50:53]
	v_mfma_f32_16x16x32_bf16 v[38:41], v[156:159], v[186:189], v[38:41]
	v_mfma_f32_16x16x32_bf16 v[34:37], v[170:173], v[186:189], v[34:37]
	v_mfma_f32_16x16x32_bf16 v[22:25], v[156:159], v[194:197], v[22:25]
	v_mfma_f32_16x16x32_bf16 v[18:21], v[170:173], v[194:197], v[18:21]
	v_mfma_f32_16x16x32_bf16 v[6:9], v[156:159], v[202:205], v[6:9]
	v_mfma_f32_16x16x32_bf16 v[2:5], v[170:173], v[202:205], v[2:5]
	s_setprio 0
	s_barrier
	s_add_u32 s25, s25, 0x100
	s_addc_u32 s27, s27, 0
	s_cmp_ge_i32 s53, s4
	s_mov_b64 s[34:35], s[40:41]
	s_mov_b32 s51, s53
	s_cbranch_scc0 .LBB0_768
	s_and_b64 vcc, exec, s[48:49]
	s_cbranch_vccz .LBB0_771

; #define PG8_STAGE(bufoff, gbase, voff) do { _Pragma("unroll") for (int _i = 0; _i < 2; ++_i) \
;         __builtin_amdgcn_global_load_lds((const unsigned*)((const char*)(gbase) + (voff)[_i]), (PG8_LAS unsigned*)(lds + (bufoff) + ldsw + _i * 8192), 16, 0, 0); } while (0)
; #define PG8_LDA(dst, b, h) do { _Pragma("unroll") for (int m = 0; m < 4; ++m) _Pragma("unroll") for (int k = 0; k < 2; ++k) dst[m][k] = *(const PG8_LAS bf16x8*)(lds + PG8_SA(b, h) + aoff + m * 2048 + k * 1024); } while (0)
; #define PG8_LDB(dst, b, h) do { _Pragma("unroll") for (int n = 0; n < 2; ++n) _Pragma("unroll") for (int k = 0; k < 2; ++k) dst[n][k] = *(const PG8_LAS bf16x8*)(lds + PG8_SB(b, h) + boff + n * 2048 + k * 1024); } while (0)
; #define PG8_MMA(ai, bj, At, Bt) do { __builtin_amdgcn_s_setprio(1); _Pragma("unroll") for (int m = 0; m < 4; ++m) _Pragma("unroll") for (int n = 0; n < 2; ++n) _Pragma("unroll") for (int k = 0; k < 2; ++k) \
;         acc[ai][bj][m][n] = __builtin_amdgcn_mfma_f32_16x16x32_bf16(Bt[n][k], At[m][k], acc[ai][bj][m][n], 0, 0, 0); __builtin_amdgcn_s_setprio(0); } while (0)
; #define PG8_WAIT_V(n) asm volatile("s_waitcnt vmcnt(" #n ")" ::: "memory")
; #define PG8_WAIT_L(n) asm volatile("s_waitcnt lgkmcnt(" #n ")" ::: "memory")
; template <class Epi, class Sched, bool ALIGN_EPI = false, bool SP2 = false>
; __device__ __forceinline__ void gemm_phase(PG8_LAS unsigned char* lds, const Gemm g, const Sched& S, const Epi& E) {
;     ...
;             const bool last = (t == unt - 2);
;             const char* a1 = cA + (size_t)(t + 1) * kstep;
;             const char* a2 = last ? nA : cA + (size_t)(t + 2) * kstep; const char* b2 = last ? nB : cB + (size_t)(t + 2) * kstep;
;             const char* a3 = a2 + kstep; const char* b3 = b2 + kstep;
;             if (last && has_next) S.a_ready(nxt);
;             if constexpr (SP2) {
;             PG8_LDB(B0, 0, 0); PG8_LDB(B1, 0, 1); PG8_SCHED; PG8_LDA(At, 0, 0); PG8_STAGE(PG8_SA(1, 1), a1 + hstep, voffA);
;             PG8_WAIT_V(8); PG8_WAIT_L(0); PG8_BAR; PG8_MMA(0, 0, At, B0); PG8_MMA(0, 1, At, B1); PG8_BAR; PG8_SCHED;
;             PG8_LDA(At, 0, 1); PG8_STAGE(PG8_SB(0, 0), b2, voffB); PG8_STAGE(PG8_SB(0, 1), b2 + hstep, voffB); PG8_STAGE(PG8_SA(0, 0), a2, voffA);
;             PG8_WAIT_V(8); PG8_WAIT_L(0); PG8_BAR; PG8_MMA(1, 0, At, B0); PG8_MMA(1, 1, At, B1); PG8_BAR; PG8_SCHED;
.LBB0_1026:
	s_add_u32 s6, s46, 0xfffc0080
	s_addc_u32 s7, s47, -1
	s_add_i32 s76, 0, 0x10000
	s_cmp_eq_u32 s71, 12
	s_cselect_b32 s51, s5, s7
	s_cselect_b32 s50, s35, s6
	v_add_u32_e32 v140, s76, v143
	s_cselect_b32 s49, s31, s70
	s_cselect_b32 s48, s68, s69
	s_add_i32 s77, 0, 0x14000
	ds_read_b128 v[146:149], v140
	ds_read_b128 v[150:153], v140 offset:1024
	ds_read_b128 v[154:157], v140 offset:2048
	ds_read_b128 v[158:161], v140 offset:3072
	v_add_u32_e32 v140, s77, v143
	ds_read_b128 v[162:165], v140
	ds_read_b128 v[166:169], v140 offset:1024
	ds_read_b128 v[170:173], v140 offset:2048
	ds_read_b128 v[174:177], v140 offset:3072
	s_add_i32 m0, s45, 0xc000
	ds_read_b128 v[178:181], v145
	ds_read_b128 v[182:185], v145 offset:1024
	ds_read_b128 v[186:189], v145 offset:2048
	ds_read_b128 v[190:193], v145 offset:3072
	ds_read_b128 v[194:197], v145 offset:4096
	ds_read_b128 v[198:201], v145 offset:5120
	ds_read_b128 v[202:205], v145 offset:6144
	ds_read_b128 v[212:215], v145 offset:7168
	global_load_lds_dwordx4 v136, s[46:47]
	s_add_i32 m0, s45, 0xe000
	s_nop 0
	global_load_lds_dwordx4 v138, s[46:47]
	s_waitcnt vmcnt(8) lgkmcnt(0)
	s_barrier
	s_setprio 1
	v_mfma_f32_16x16x32_bf16 v[126:129], v[146:149], v[178:181], v[126:129]
	v_mfma_f32_16x16x32_bf16 v[122:125], v[154:157], v[178:181], v[122:125]
	v_mfma_f32_16x16x32_bf16 v[110:113], v[146:149], v[186:189], v[110:113]
	v_mfma_f32_16x16x32_bf16 v[106:109], v[154:157], v[186:189], v[106:109]
	v_mfma_f32_16x16x32_bf16 v[94:97], v[146:149], v[194:197], v[94:97]
	v_mfma_f32_16x16x32_bf16 v[90:93], v[154:157], v[194:197], v[90:93]
	v_mfma_f32_16x16x32_bf16 v[78:81], v[146:149], v[202:205], v[78:81]
	v_mfma_f32_16x16x32_bf16 v[74:77], v[154:157], v[202:205], v[74:77]
	v_mfma_f32_16x16x32_bf16 v[126:129], v[150:153], v[182:185], v[126:129]
	v_mfma_f32_16x16x32_bf16 v[122:125], v[158:161], v[182:185], v[122:125]
	v_mfma_f32_16x16x32_bf16 v[110:113], v[150:153], v[190:193], v[110:113]
	v_mfma_f32_16x16x32_bf16 v[106:109], v[158:161], v[190:193], v[106:109]
	v_mfma_f32_16x16x32_bf16 v[94:97], v[150:153], v[198:201], v[94:97]
	v_mfma_f32_16x16x32_bf16 v[90:93], v[158:161], v[198:201], v[90:93]
	v_mfma_f32_16x16x32_bf16 v[78:81], v[150:153], v[212:215], v[78:81]
	v_mfma_f32_16x16x32_bf16 v[74:77], v[158:161], v[212:215], v[74:77]
	v_mfma_f32_16x16x32_bf16 v[118:121], v[162:165], v[178:181], v[118:121]
	v_mfma_f32_16x16x32_bf16 v[114:117], v[170:173], v[178:181], v[114:117]
	v_mfma_f32_16x16x32_bf16 v[102:105], v[162:165], v[186:189], v[102:105]
	v_mfma_f32_16x16x32_bf16 v[98:101], v[170:173], v[186:189], v[98:101]
	v_mfma_f32_16x16x32_bf16 v[86:89], v[162:165], v[194:197], v[86:89]
	v_mfma_f32_16x16x32_bf16 v[82:85], v[170:173], v[194:197], v[82:85]
	v_mfma_f32_16x16x32_bf16 v[70:73], v[162:165], v[202:205], v[70:73]
	v_mfma_f32_16x16x32_bf16 v[66:69], v[170:173], v[202:205], v[66:69]
	v_mfma_f32_16x16x32_bf16 v[118:121], v[166:169], v[182:185], v[118:121]
	v_mfma_f32_16x16x32_bf16 v[114:117], v[174:177], v[182:185], v[114:117]
	v_mfma_f32_16x16x32_bf16 v[102:105], v[166:169], v[190:193], v[102:105]
	v_mfma_f32_16x16x32_bf16 v[98:101], v[174:177], v[190:193], v[98:101]
	v_mfma_f32_16x16x32_bf16 v[86:89], v[166:169], v[198:201], v[86:89]
	v_mfma_f32_16x16x32_bf16 v[82:85], v[174:177], v[198:201], v[82:85]
	v_mfma_f32_16x16x32_bf16 v[70:73], v[166:169], v[212:215], v[70:73]
	v_mfma_f32_16x16x32_bf16 v[66:69], v[174:177], v[212:215], v[66:69]
	s_setprio 0
	s_barrier
	s_add_i32 s6, s76, s60
	s_add_u32 s98, s48, s22
	s_addc_u32 s99, s49, s23
	s_mov_b32 m0, s6
	ds_read_b128 v[178:181], v145 offset:16384
	ds_read_b128 v[182:185], v145 offset:17408
	ds_read_b128 v[186:189], v145 offset:18432
	ds_read_b128 v[190:193], v145 offset:19456
	ds_read_b128 v[194:197], v145 offset:20480
	ds_read_b128 v[198:201], v145 offset:21504
	ds_read_b128 v[202:205], v145 offset:22528
	ds_read_b128 v[212:215], v145 offset:23552
	global_load_lds_dwordx4 v0, s[48:49]
	s_add_i32 m0, s6, 0x2000
	s_add_u32 s6, s48, 0x40000
	s_addc_u32 s7, s49, 0
	s_add_i32 s76, s77, s60
	global_load_lds_dwordx4 v130, s[48:49]
	s_mov_b32 m0, s76
	s_add_u32 s100, s50, s22
	s_addc_u32 s101, s51, s23
	global_load_lds_dwordx4 v0, s[6:7]
	s_add_i32 m0, s76, 0x2000
	s_nop 0
	global_load_lds_dwordx4 v130, s[6:7]
	s_mov_b32 m0, s45
	s_nop 0
	global_load_lds_dwordx4 v134, s[50:51]
	s_mov_b32 m0, s62
	s_nop 0
	global_load_lds_dwordx4 v132, s[50:51]
	s_waitcnt vmcnt(8) lgkmcnt(0)
	s_barrier
	s_setprio 1
	v_mfma_f32_16x16x32_bf16 v[62:65], v[146:149], v[178:181], v[62:65]
	v_mfma_f32_16x16x32_bf16 v[58:61], v[154:157], v[178:181], v[58:61]
	v_mfma_f32_16x16x32_bf16 v[46:49], v[146:149], v[186:189], v[46:49]
	v_mfma_f32_16x16x32_bf16 v[42:45], v[154:157], v[186:189], v[42:45]
	v_mfma_f32_16x16x32_bf16 v[30:33], v[146:149], v[194:197], v[30:33]
	v_mfma_f32_16x16x32_bf16 v[26:29], v[154:157], v[194:197], v[26:29]
	v_mfma_f32_16x16x32_bf16 v[14:17], v[146:149], v[202:205], v[14:17]
	v_mfma_f32_16x16x32_bf16 v[10:13], v[154:157], v[202:205], v[10:13]
	v_mfma_f32_16x16x32_bf16 v[62:65], v[150:153], v[182:185], v[62:65]
	v_mfma_f32_16x16x32_bf16 v[58:61], v[158:161], v[182:185], v[58:61]
	v_mfma_f32_16x16x32_bf16 v[46:49], v[150:153], v[190:193], v[46:49]
	v_mfma_f32_16x16x32_bf16 v[42:45], v[158:161], v[190:193], v[42:45]
	v_mfma_f32_16x16x32_bf16 v[30:33], v[150:153], v[198:201], v[30:33]
	v_mfma_f32_16x16x32_bf16 v[26:29], v[158:161], v[198:201], v[26:29]
	v_mfma_f32_16x16x32_bf16 v[14:17], v[150:153], v[212:215], v[14:17]
	v_mfma_f32_16x16x32_bf16 v[10:13], v[158:161], v[212:215], v[10:13]
	v_mfma_f32_16x16x32_bf16 v[54:57], v[162:165], v[178:181], v[54:57]
	v_mfma_f32_16x16x32_bf16 v[50:53], v[170:173], v[178:181], v[50:53]
	v_mfma_f32_16x16x32_bf16 v[38:41], v[162:165], v[186:189], v[38:41]
	v_mfma_f32_16x16x32_bf16 v[34:37], v[170:173], v[186:189], v[34:37]
	v_mfma_f32_16x16x32_bf16 v[22:25], v[162:165], v[194:197], v[22:25]
	v_mfma_f32_16x16x32_bf16 v[18:21], v[170:173], v[194:197], v[18:21]
	v_mfma_f32_16x16x32_bf16 v[6:9], v[162:165], v[202:205], v[6:9]
	v_mfma_f32_16x16x32_bf16 v[2:5], v[170:173], v[202:205], v[2:5]
	v_mfma_f32_16x16x32_bf16 v[54:57], v[166:169], v[182:185], v[54:57]
	v_mfma_f32_16x16x32_bf16 v[50:53], v[174:177], v[182:185], v[50:53]
	v_mfma_f32_16x16x32_bf16 v[38:41], v[166:169], v[190:193], v[38:41]
	v_mfma_f32_16x16x32_bf16 v[34:37], v[174:177], v[190:193], v[34:37]
	v_mfma_f32_16x16x32_bf16 v[22:25], v[166:169], v[198:201], v[22:25]
	v_mfma_f32_16x16x32_bf16 v[18:21], v[174:177], v[198:201], v[18:21]
	v_mfma_f32_16x16x32_bf16 v[6:9], v[166:169], v[212:215], v[6:9]
	v_mfma_f32_16x16x32_bf16 v[2:5], v[174:177], v[212:215], v[2:5]
	s_setprio 0
	s_barrier
; #define PG8_STAGE(bufoff, gbase, voff) do { _Pragma("unroll") for (int _i = 0; _i < 2; ++_i) \
;         __builtin_amdgcn_global_load_lds((const unsigned*)((const char*)(gbase) + (voff)[_i]), (PG8_LAS unsigned*)(lds + (bufoff) + ldsw + _i * 8192), 16, 0, 0); } while (0)
; #define PG8_LDA(dst, b, h) do { _Pragma("unroll") for (int m = 0; m < 4; ++m) _Pragma("unroll") for (int k = 0; k < 2; ++k) dst[m][k] = *(const PG8_LAS bf16x8*)(lds + PG8_SA(b, h) + aoff + m * 2048 + k * 1024); } while (0)
; #define PG8_LDB(dst, b, h) do { _Pragma("unroll") for (int n = 0; n < 2; ++n) _Pragma("unroll") for (int k = 0; k < 2; ++k) dst[n][k] = *(const PG8_LAS bf16x8*)(lds + PG8_SB(b, h) + boff + n * 2048 + k * 1024); } while (0)
; #define PG8_MMA(ai, bj, At, Bt) do { __builtin_amdgcn_s_setprio(1); _Pragma("unroll") for (int m = 0; m < 4; ++m) _Pragma("unroll") for (int n = 0; n < 2; ++n) _Pragma("unroll") for (int k = 0; k < 2; ++k) \
;         acc[ai][bj][m][n] = __builtin_amdgcn_mfma_f32_16x16x32_bf16(Bt[n][k], At[m][k], acc[ai][bj][m][n], 0, 0, 0); __builtin_amdgcn_s_setprio(0); } while (0)
; #define PG8_WAIT_V(n) asm volatile("s_waitcnt vmcnt(" #n ")" ::: "memory")
; #define PG8_WAIT_L(n) asm volatile("s_waitcnt lgkmcnt(" #n ")" ::: "memory")
; #define PG8_BAR __builtin_amdgcn_s_barrier()
; #define PG8_SCHED __builtin_amdgcn_sched_barrier(0)
; template <class Epi, class Sched, bool ALIGN_EPI = false, bool SP2 = false>
; __device__ __forceinline__ void gemm_phase(PG8_LAS unsigned char* lds, const Gemm g, const Sched& S, const Epi& E) {
;     ...
;             PG8_LDB(B0, 1, 0); PG8_LDB(B1, 1, 1); PG8_SCHED; PG8_LDA(At, 1, 0); PG8_STAGE(PG8_SA(0, 1), a2 + hstep, voffA);
;             PG8_WAIT_V(8); PG8_WAIT_L(0); PG8_BAR; PG8_MMA(0, 0, At, B0); PG8_MMA(0, 1, At, B1); PG8_BAR; PG8_SCHED;
;             PG8_LDA(At, 1, 1); PG8_STAGE(PG8_SB(1, 0), b3, voffB); PG8_STAGE(PG8_SB(1, 1), b3 + hstep, voffB); PG8_STAGE(PG8_SA(1, 0), a3, voffA);
;             PG8_WAIT_V(8); PG8_WAIT_L(0); PG8_BAR; PG8_MMA(1, 0, At, B0); PG8_MMA(1, 1, At, B1); PG8_BAR; PG8_SCHED;
;     ...
;         if constexpr (ALIGN_EPI) { if (wr == 0) PG8_BAR; }
	s_add_i32 s76, 0, 0x18000
	s_add_i32 s77, 0, 0x1c000
	v_add_u32_e32 v158, s76, v143
	v_add_u32_e32 v174, s77, v143
	ds_read_b128 v[146:149], v158
	ds_read_b128 v[150:153], v158 offset:1024
	ds_read_b128 v[154:157], v158 offset:2048
	ds_read_b128 v[158:161], v158 offset:3072
	ds_read_b128 v[162:165], v174
	ds_read_b128 v[166:169], v174 offset:1024
	ds_read_b128 v[170:173], v174 offset:2048
	ds_read_b128 v[174:177], v174 offset:3072
	s_add_u32 s6, s50, 0x40000
	s_addc_u32 s7, s51, 0
	s_mov_b32 m0, s63
	ds_read_b128 v[178:181], v145 offset:32768
	ds_read_b128 v[182:185], v145 offset:33792
	ds_read_b128 v[186:189], v145 offset:34816
	ds_read_b128 v[190:193], v145 offset:35840
	ds_read_b128 v[194:197], v145 offset:36864
	ds_read_b128 v[198:201], v145 offset:37888
	ds_read_b128 v[202:205], v145 offset:38912
	ds_read_b128 v[212:215], v145 offset:39936
	global_load_lds_dwordx4 v134, s[6:7]
	s_mov_b32 m0, s64
	s_nop 0
	global_load_lds_dwordx4 v132, s[6:7]
	s_waitcnt vmcnt(8) lgkmcnt(0)
	s_barrier
	s_setprio 1
	v_mfma_f32_16x16x32_bf16 v[126:129], v[146:149], v[178:181], v[126:129]
	v_mfma_f32_16x16x32_bf16 v[122:125], v[154:157], v[178:181], v[122:125]
	v_mfma_f32_16x16x32_bf16 v[110:113], v[146:149], v[186:189], v[110:113]
	v_mfma_f32_16x16x32_bf16 v[106:109], v[154:157], v[186:189], v[106:109]
	v_mfma_f32_16x16x32_bf16 v[94:97], v[146:149], v[194:197], v[94:97]
	v_mfma_f32_16x16x32_bf16 v[90:93], v[154:157], v[194:197], v[90:93]
	v_mfma_f32_16x16x32_bf16 v[78:81], v[146:149], v[202:205], v[78:81]
	v_mfma_f32_16x16x32_bf16 v[74:77], v[154:157], v[202:205], v[74:77]
	v_mfma_f32_16x16x32_bf16 v[126:129], v[150:153], v[182:185], v[126:129]
	v_mfma_f32_16x16x32_bf16 v[122:125], v[158:161], v[182:185], v[122:125]
	v_mfma_f32_16x16x32_bf16 v[110:113], v[150:153], v[190:193], v[110:113]
	v_mfma_f32_16x16x32_bf16 v[106:109], v[158:161], v[190:193], v[106:109]
	v_mfma_f32_16x16x32_bf16 v[94:97], v[150:153], v[198:201], v[94:97]
	v_mfma_f32_16x16x32_bf16 v[90:93], v[158:161], v[198:201], v[90:93]
	v_mfma_f32_16x16x32_bf16 v[78:81], v[150:153], v[212:215], v[78:81]
	v_mfma_f32_16x16x32_bf16 v[74:77], v[158:161], v[212:215], v[74:77]
	v_mfma_f32_16x16x32_bf16 v[118:121], v[162:165], v[178:181], v[118:121]
	v_mfma_f32_16x16x32_bf16 v[114:117], v[170:173], v[178:181], v[114:117]
	v_mfma_f32_16x16x32_bf16 v[102:105], v[162:165], v[186:189], v[102:105]
	v_mfma_f32_16x16x32_bf16 v[98:101], v[170:173], v[186:189], v[98:101]
	v_mfma_f32_16x16x32_bf16 v[86:89], v[162:165], v[194:197], v[86:89]
	v_mfma_f32_16x16x32_bf16 v[82:85], v[170:173], v[194:197], v[82:85]
	v_mfma_f32_16x16x32_bf16 v[70:73], v[162:165], v[202:205], v[70:73]
	v_mfma_f32_16x16x32_bf16 v[66:69], v[170:173], v[202:205], v[66:69]
	v_mfma_f32_16x16x32_bf16 v[118:121], v[166:169], v[182:185], v[118:121]
	v_mfma_f32_16x16x32_bf16 v[114:117], v[174:177], v[182:185], v[114:117]
	v_mfma_f32_16x16x32_bf16 v[102:105], v[166:169], v[190:193], v[102:105]
	v_mfma_f32_16x16x32_bf16 v[98:101], v[174:177], v[190:193], v[98:101]
	v_mfma_f32_16x16x32_bf16 v[86:89], v[166:169], v[198:201], v[86:89]
	v_mfma_f32_16x16x32_bf16 v[82:85], v[174:177], v[198:201], v[82:85]
	v_mfma_f32_16x16x32_bf16 v[70:73], v[166:169], v[212:215], v[70:73]
	v_mfma_f32_16x16x32_bf16 v[66:69], v[174:177], v[212:215], v[66:69]
	s_setprio 0
	s_barrier
	s_add_i32 s6, s76, s60
	s_mov_b32 m0, s6
	ds_read_b128 v[178:181], v145 offset:49152
	ds_read_b128 v[182:185], v145 offset:50176
	ds_read_b128 v[186:189], v145 offset:51200
	ds_read_b128 v[190:193], v145 offset:52224
	ds_read_b128 v[194:197], v145 offset:53248
	ds_read_b128 v[198:201], v145 offset:54272
	ds_read_b128 v[202:205], v145 offset:55296
	ds_read_b128 v[212:215], v145 offset:56320
	global_load_lds_dwordx4 v0, s[98:99]
	s_add_i32 m0, s6, 0x2000
	s_add_u32 s6, s48, 0x40080
	s_addc_u32 s7, s49, 0
	s_add_i32 s48, s77, s60
	global_load_lds_dwordx4 v130, s[98:99]
	s_mov_b32 m0, s48
	s_nop 0
	global_load_lds_dwordx4 v0, s[6:7]
	s_add_i32 m0, s48, 0x2000
	s_nop 0
	global_load_lds_dwordx4 v130, s[6:7]
	s_mov_b32 m0, s65
	s_nop 0
	global_load_lds_dwordx4 v134, s[100:101]
	s_mov_b32 m0, s66
	s_nop 0
	global_load_lds_dwordx4 v132, s[100:101]
	s_waitcnt vmcnt(8) lgkmcnt(0)
	s_barrier
	s_setprio 1
	v_mfma_f32_16x16x32_bf16 v[62:65], v[146:149], v[178:181], v[62:65]
	v_mfma_f32_16x16x32_bf16 v[58:61], v[154:157], v[178:181], v[58:61]
	v_mfma_f32_16x16x32_bf16 v[46:49], v[146:149], v[186:189], v[46:49]
	v_mfma_f32_16x16x32_bf16 v[42:45], v[154:157], v[186:189], v[42:45]
	v_mfma_f32_16x16x32_bf16 v[30:33], v[146:149], v[194:197], v[30:33]
	v_mfma_f32_16x16x32_bf16 v[26:29], v[154:157], v[194:197], v[26:29]
	v_mfma_f32_16x16x32_bf16 v[14:17], v[146:149], v[202:205], v[14:17]
	v_mfma_f32_16x16x32_bf16 v[10:13], v[154:157], v[202:205], v[10:13]
	v_mfma_f32_16x16x32_bf16 v[62:65], v[150:153], v[182:185], v[62:65]
	v_mfma_f32_16x16x32_bf16 v[58:61], v[158:161], v[182:185], v[58:61]
	v_mfma_f32_16x16x32_bf16 v[46:49], v[150:153], v[190:193], v[46:49]
	v_mfma_f32_16x16x32_bf16 v[42:45], v[158:161], v[190:193], v[42:45]
	v_mfma_f32_16x16x32_bf16 v[30:33], v[150:153], v[198:201], v[30:33]
	v_mfma_f32_16x16x32_bf16 v[26:29], v[158:161], v[198:201], v[26:29]
	v_mfma_f32_16x16x32_bf16 v[14:17], v[150:153], v[212:215], v[14:17]
	v_mfma_f32_16x16x32_bf16 v[10:13], v[158:161], v[212:215], v[10:13]
	v_mfma_f32_16x16x32_bf16 v[54:57], v[162:165], v[178:181], v[54:57]
	v_mfma_f32_16x16x32_bf16 v[50:53], v[170:173], v[178:181], v[50:53]
	v_mfma_f32_16x16x32_bf16 v[38:41], v[162:165], v[186:189], v[38:41]
	v_mfma_f32_16x16x32_bf16 v[34:37], v[170:173], v[186:189], v[34:37]
	v_mfma_f32_16x16x32_bf16 v[22:25], v[162:165], v[194:197], v[22:25]
	v_mfma_f32_16x16x32_bf16 v[18:21], v[170:173], v[194:197], v[18:21]
	v_mfma_f32_16x16x32_bf16 v[6:9], v[162:165], v[202:205], v[6:9]
	v_mfma_f32_16x16x32_bf16 v[2:5], v[170:173], v[202:205], v[2:5]
	v_mfma_f32_16x16x32_bf16 v[54:57], v[166:169], v[182:185], v[54:57]
	v_mfma_f32_16x16x32_bf16 v[50:53], v[174:177], v[182:185], v[50:53]
	v_mfma_f32_16x16x32_bf16 v[38:41], v[166:169], v[190:193], v[38:41]
	v_mfma_f32_16x16x32_bf16 v[34:37], v[174:177], v[190:193], v[34:37]
	v_mfma_f32_16x16x32_bf16 v[22:25], v[166:169], v[198:201], v[22:25]
	v_mfma_f32_16x16x32_bf16 v[18:21], v[174:177], v[198:201], v[18:21]
	v_mfma_f32_16x16x32_bf16 v[6:9], v[166:169], v[212:215], v[6:9]
	v_mfma_f32_16x16x32_bf16 v[2:5], v[174:177], v[212:215], v[2:5]
	s_setprio 0
	s_barrier
	s_add_i32 s71, s71, 2
	s_add_u32 s46, s46, 0x100
	s_addc_u32 s47, s47, 0
	s_add_u32 s69, s69, 0x100
	s_addc_u32 s70, s70, 0
	s_cmp_gt_u32 s71, 13
	s_cbranch_scc0 .LBB0_1026
	s_and_b64 vcc, exec, s[26:27]
	s_cbranch_vccz .LBB0_1029
	s_barrier

; #define PG8_STAGE(bufoff, gbase, voff) do { _Pragma("unroll") for (int _i = 0; _i < 2; ++_i) \
;         __builtin_amdgcn_global_load_lds((const unsigned*)((const char*)(gbase) + (voff)[_i]), (PG8_LAS unsigned*)(lds + (bufoff) + ldsw + _i * 8192), 16, 0, 0); } while (0)
; #define PG8_LDA(dst, b, h) do { _Pragma("unroll") for (int m = 0; m < 4; ++m) _Pragma("unroll") for (int k = 0; k < 2; ++k) dst[m][k] = *(const PG8_LAS bf16x8*)(lds + PG8_SA(b, h) + aoff + m * 2048 + k * 1024); } while (0)
; #define PG8_LDB(dst, b, h) do { _Pragma("unroll") for (int n = 0; n < 2; ++n) _Pragma("unroll") for (int k = 0; k < 2; ++k) dst[n][k] = *(const PG8_LAS bf16x8*)(lds + PG8_SB(b, h) + boff + n * 2048 + k * 1024); } while (0)
; #define PG8_MMA(ai, bj, At, Bt) do { __builtin_amdgcn_s_setprio(1); _Pragma("unroll") for (int m = 0; m < 4; ++m) _Pragma("unroll") for (int n = 0; n < 2; ++n) _Pragma("unroll") for (int k = 0; k < 2; ++k) \
;         acc[ai][bj][m][n] = __builtin_amdgcn_mfma_f32_16x16x32_bf16(Bt[n][k], At[m][k], acc[ai][bj][m][n], 0, 0, 0); __builtin_amdgcn_s_setprio(0); } while (0)
; #define PG8_WAIT_V(n) asm volatile("s_waitcnt vmcnt(" #n ")" ::: "memory")
; #define PG8_WAIT_L(n) asm volatile("s_waitcnt lgkmcnt(" #n ")" ::: "memory")
; #define PG8_BAR __builtin_amdgcn_s_barrier()
; #define PG8_SCHED __builtin_amdgcn_sched_barrier(0)
; template <class Epi, class Sched, bool ALIGN_EPI = false, bool SP2 = false>
; __device__ __forceinline__ void gemm_phase(PG8_LAS unsigned char* lds, const Gemm g, const Sched& S, const Epi& E) {
;     ...
;             PG8_LDB(B0, 0, 0); PG8_LDB(B1, 0, 1); PG8_SCHED; PG8_LDA(At, 0, 0); PG8_STAGE(PG8_SA(1, 1), a1 + hstep, voffA);
;             PG8_WAIT_V(8); PG8_WAIT_L(0); PG8_BAR; PG8_MMA(0, 0, At, B0); PG8_MMA(0, 1, At, B1); PG8_BAR; PG8_SCHED;
;             PG8_LDA(At, 0, 1); PG8_STAGE(PG8_SB(0, 0), b2, voffB); PG8_STAGE(PG8_SB(0, 1), b2 + hstep, voffB); PG8_STAGE(PG8_SA(0, 0), a2, voffA);
;             PG8_WAIT_V(8); PG8_WAIT_L(0); PG8_BAR; PG8_MMA(1, 0, At, B0); PG8_MMA(1, 1, At, B1); PG8_BAR; PG8_SCHED;
.LBB0_1122:
	s_add_i32 s51, s49, 2
	s_add_u32 s40, s34, 0x100
	s_addc_u32 s41, s35, 0
	s_add_i32 s6, 0, 0x10000
	s_cmp_eq_u32 s5, s49
	s_cselect_b32 s61, s55, s41
	s_cselect_b32 s60, s54, s40
	s_cselect_b32 s59, s57, s27
	s_cselect_b32 s58, s56, s25
	s_add_i32 s49, 0, 0x14000
	s_waitcnt vmcnt(0)
	v_add_u32_e32 v78, s6, v163
	v_add_u32_e32 v160, s49, v163
	ds_read_b128 v[54:57], v78
	ds_read_b128 v[62:65], v78 offset:1024
	ds_read_b128 v[70:73], v78 offset:2048
	ds_read_b128 v[78:81], v78 offset:3072
	ds_read_b128 v[152:155], v160
	ds_read_b128 v[156:159], v160 offset:1024
	ds_read_b128 v[166:169], v160 offset:2048
	ds_read_b128 v[170:173], v160 offset:3072
	s_add_i32 m0, s43, 0xc000
	ds_read_b128 v[174:177], v165
	ds_read_b128 v[178:181], v165 offset:1024
	ds_read_b128 v[182:185], v165 offset:2048
	ds_read_b128 v[186:189], v165 offset:3072
	ds_read_b128 v[190:193], v165 offset:4096
	ds_read_b128 v[194:197], v165 offset:5120
	ds_read_b128 v[198:201], v165 offset:6144
	ds_read_b128 v[202:205], v165 offset:7168
	global_load_lds_dwordx4 v148, s[34:35]
	s_add_i32 m0, s43, 0xe000
	s_nop 0
	global_load_lds_dwordx4 v150, s[34:35]
	s_waitcnt vmcnt(8) lgkmcnt(0)
	s_barrier
	s_setprio 1
	v_mfma_f32_16x16x32_bf16 v[142:145], v[54:57], v[174:177], v[142:145]
	v_mfma_f32_16x16x32_bf16 v[138:141], v[70:73], v[174:177], v[138:141]
	v_mfma_f32_16x16x32_bf16 v[126:129], v[54:57], v[182:185], v[126:129]
	v_mfma_f32_16x16x32_bf16 v[122:125], v[70:73], v[182:185], v[122:125]
	v_mfma_f32_16x16x32_bf16 v[110:113], v[54:57], v[190:193], v[110:113]
	v_mfma_f32_16x16x32_bf16 v[106:109], v[70:73], v[190:193], v[106:109]
	v_mfma_f32_16x16x32_bf16 v[94:97], v[54:57], v[198:201], v[94:97]
	v_mfma_f32_16x16x32_bf16 v[90:93], v[70:73], v[198:201], v[90:93]
	v_mfma_f32_16x16x32_bf16 v[142:145], v[62:65], v[178:181], v[142:145]
	v_mfma_f32_16x16x32_bf16 v[138:141], v[78:81], v[178:181], v[138:141]
	v_mfma_f32_16x16x32_bf16 v[126:129], v[62:65], v[186:189], v[126:129]
	v_mfma_f32_16x16x32_bf16 v[122:125], v[78:81], v[186:189], v[122:125]
	v_mfma_f32_16x16x32_bf16 v[110:113], v[62:65], v[194:197], v[110:113]
	v_mfma_f32_16x16x32_bf16 v[106:109], v[78:81], v[194:197], v[106:109]
	v_mfma_f32_16x16x32_bf16 v[94:97], v[62:65], v[202:205], v[94:97]
	v_mfma_f32_16x16x32_bf16 v[90:93], v[78:81], v[202:205], v[90:93]
	v_mfma_f32_16x16x32_bf16 v[134:137], v[152:155], v[174:177], v[134:137]
	v_mfma_f32_16x16x32_bf16 v[130:133], v[166:169], v[174:177], v[130:133]
	v_mfma_f32_16x16x32_bf16 v[118:121], v[152:155], v[182:185], v[118:121]
	v_mfma_f32_16x16x32_bf16 v[114:117], v[166:169], v[182:185], v[114:117]
	v_mfma_f32_16x16x32_bf16 v[102:105], v[152:155], v[190:193], v[102:105]
	v_mfma_f32_16x16x32_bf16 v[98:101], v[166:169], v[190:193], v[98:101]
	v_mfma_f32_16x16x32_bf16 v[86:89], v[152:155], v[198:201], v[86:89]
	v_mfma_f32_16x16x32_bf16 v[82:85], v[166:169], v[198:201], v[82:85]
	v_mfma_f32_16x16x32_bf16 v[134:137], v[156:159], v[178:181], v[134:137]
	v_mfma_f32_16x16x32_bf16 v[130:133], v[170:173], v[178:181], v[130:133]
	v_mfma_f32_16x16x32_bf16 v[118:121], v[156:159], v[186:189], v[118:121]
	v_mfma_f32_16x16x32_bf16 v[114:117], v[170:173], v[186:189], v[114:117]
	v_mfma_f32_16x16x32_bf16 v[102:105], v[156:159], v[194:197], v[102:105]
	v_mfma_f32_16x16x32_bf16 v[98:101], v[170:173], v[194:197], v[98:101]
	v_mfma_f32_16x16x32_bf16 v[86:89], v[156:159], v[202:205], v[86:89]
	v_mfma_f32_16x16x32_bf16 v[82:85], v[170:173], v[202:205], v[82:85]
	s_setprio 0
	s_barrier
	s_add_i32 s6, s6, s67
	s_add_u32 s98, s58, s22
	s_addc_u32 s99, s59, s23
	s_mov_b32 m0, s6
	ds_read_b128 v[174:177], v165 offset:16384
	ds_read_b128 v[178:181], v165 offset:17408
	ds_read_b128 v[182:185], v165 offset:18432
	ds_read_b128 v[186:189], v165 offset:19456
	ds_read_b128 v[190:193], v165 offset:20480
	ds_read_b128 v[194:197], v165 offset:21504
	ds_read_b128 v[198:201], v165 offset:22528
	ds_read_b128 v[202:205], v165 offset:23552
	global_load_lds_dwordx4 v0, s[58:59]
	s_add_i32 m0, s6, 0x2000
	s_add_u32 s6, s58, 0x100000
	s_addc_u32 s7, s59, 0
	s_add_i32 s34, s49, s67
	global_load_lds_dwordx4 v146, s[58:59]
	s_mov_b32 m0, s34
	s_add_u32 s100, s60, s22
	s_addc_u32 s101, s61, s23
	global_load_lds_dwordx4 v0, s[6:7]
	s_add_i32 m0, s34, 0x2000
	s_nop 0
	global_load_lds_dwordx4 v146, s[6:7]
	s_mov_b32 m0, s43
	s_nop 0
	global_load_lds_dwordx4 v0, s[60:61]
	s_mov_b32 m0, s76
	s_nop 0
	global_load_lds_dwordx4 v146, s[60:61]
	s_waitcnt vmcnt(8) lgkmcnt(0)
	s_barrier
	s_setprio 1
	v_mfma_f32_16x16x32_bf16 v[74:77], v[54:57], v[174:177], v[74:77]
	v_mfma_f32_16x16x32_bf16 v[66:69], v[70:73], v[174:177], v[66:69]
	v_mfma_f32_16x16x32_bf16 v[46:49], v[54:57], v[182:185], v[46:49]
	v_mfma_f32_16x16x32_bf16 v[42:45], v[70:73], v[182:185], v[42:45]
	v_mfma_f32_16x16x32_bf16 v[30:33], v[54:57], v[190:193], v[30:33]
	v_mfma_f32_16x16x32_bf16 v[26:29], v[70:73], v[190:193], v[26:29]
	v_mfma_f32_16x16x32_bf16 v[14:17], v[54:57], v[198:201], v[14:17]
	v_mfma_f32_16x16x32_bf16 v[10:13], v[70:73], v[198:201], v[10:13]
	v_mfma_f32_16x16x32_bf16 v[74:77], v[62:65], v[178:181], v[74:77]
	v_mfma_f32_16x16x32_bf16 v[66:69], v[78:81], v[178:181], v[66:69]
	v_mfma_f32_16x16x32_bf16 v[46:49], v[62:65], v[186:189], v[46:49]
	v_mfma_f32_16x16x32_bf16 v[42:45], v[78:81], v[186:189], v[42:45]
	v_mfma_f32_16x16x32_bf16 v[30:33], v[62:65], v[194:197], v[30:33]
	v_mfma_f32_16x16x32_bf16 v[26:29], v[78:81], v[194:197], v[26:29]
	v_mfma_f32_16x16x32_bf16 v[14:17], v[62:65], v[202:205], v[14:17]
	v_mfma_f32_16x16x32_bf16 v[10:13], v[78:81], v[202:205], v[10:13]
	v_mfma_f32_16x16x32_bf16 v[50:53], v[166:169], v[174:177], v[50:53]
	v_mfma_f32_16x16x32_bf16 v[38:41], v[152:155], v[182:185], v[38:41]
	v_mfma_f32_16x16x32_bf16 v[34:37], v[166:169], v[182:185], v[34:37]
	v_mfma_f32_16x16x32_bf16 v[22:25], v[152:155], v[190:193], v[22:25]
	v_mfma_f32_16x16x32_bf16 v[18:21], v[166:169], v[190:193], v[18:21]
	v_mfma_f32_16x16x32_bf16 v[6:9], v[152:155], v[198:201], v[6:9]
	v_mfma_f32_16x16x32_bf16 v[2:5], v[166:169], v[198:201], v[2:5]
	v_mfma_f32_16x16x32_bf16 v[54:57], v[152:155], v[174:177], v[58:61]
	v_mfma_f32_16x16x32_bf16 v[50:53], v[170:173], v[178:181], v[50:53]
	v_mfma_f32_16x16x32_bf16 v[38:41], v[156:159], v[186:189], v[38:41]
	v_mfma_f32_16x16x32_bf16 v[34:37], v[170:173], v[186:189], v[34:37]
	v_mfma_f32_16x16x32_bf16 v[22:25], v[156:159], v[194:197], v[22:25]
	v_mfma_f32_16x16x32_bf16 v[18:21], v[170:173], v[194:197], v[18:21]
	v_mfma_f32_16x16x32_bf16 v[6:9], v[156:159], v[202:205], v[6:9]
	v_mfma_f32_16x16x32_bf16 v[2:5], v[170:173], v[202:205], v[2:5]
	v_mfma_f32_16x16x32_bf16 v[54:57], v[156:159], v[178:181], v[54:57]
	s_setprio 0
	s_barrier
; #define PG8_STAGE(bufoff, gbase, voff) do { _Pragma("unroll") for (int _i = 0; _i < 2; ++_i) \
;         __builtin_amdgcn_global_load_lds((const unsigned*)((const char*)(gbase) + (voff)[_i]), (PG8_LAS unsigned*)(lds + (bufoff) + ldsw + _i * 8192), 16, 0, 0); } while (0)
; #define PG8_LDA(dst, b, h) do { _Pragma("unroll") for (int m = 0; m < 4; ++m) _Pragma("unroll") for (int k = 0; k < 2; ++k) dst[m][k] = *(const PG8_LAS bf16x8*)(lds + PG8_SA(b, h) + aoff + m * 2048 + k * 1024); } while (0)
; #define PG8_LDB(dst, b, h) do { _Pragma("unroll") for (int n = 0; n < 2; ++n) _Pragma("unroll") for (int k = 0; k < 2; ++k) dst[n][k] = *(const PG8_LAS bf16x8*)(lds + PG8_SB(b, h) + boff + n * 2048 + k * 1024); } while (0)
; #define PG8_MMA(ai, bj, At, Bt) do { __builtin_amdgcn_s_setprio(1); _Pragma("unroll") for (int m = 0; m < 4; ++m) _Pragma("unroll") for (int n = 0; n < 2; ++n) _Pragma("unroll") for (int k = 0; k < 2; ++k) \
;         acc[ai][bj][m][n] = __builtin_amdgcn_mfma_f32_16x16x32_bf16(Bt[n][k], At[m][k], acc[ai][bj][m][n], 0, 0, 0); __builtin_amdgcn_s_setprio(0); } while (0)
; #define PG8_WAIT_V(n) asm volatile("s_waitcnt vmcnt(" #n ")" ::: "memory")
; #define PG8_WAIT_L(n) asm volatile("s_waitcnt lgkmcnt(" #n ")" ::: "memory")
; #define PG8_BAR __builtin_amdgcn_s_barrier()
; #define PG8_SCHED __builtin_amdgcn_sched_barrier(0)
; template <class Epi, class Sched, bool ALIGN_EPI = false, bool SP2 = false>
; __device__ __forceinline__ void gemm_phase(PG8_LAS unsigned char* lds, const Gemm g, const Sched& S, const Epi& E) {
;     ...
;         for (int t = 0; t < unt; t += 2) {
;     ...
;             PG8_LDB(B0, 1, 0); PG8_LDB(B1, 1, 1); PG8_SCHED; PG8_LDA(At, 1, 0); PG8_STAGE(PG8_SA(0, 1), a2 + hstep, voffA);
;             PG8_WAIT_V(8); PG8_WAIT_L(0); PG8_BAR; PG8_MMA(0, 0, At, B0); PG8_MMA(0, 1, At, B1); PG8_BAR; PG8_SCHED;
;             PG8_LDA(At, 1, 1); PG8_STAGE(PG8_SB(1, 0), b3, voffB); PG8_STAGE(PG8_SB(1, 1), b3 + hstep, voffB); PG8_STAGE(PG8_SA(1, 0), a3, voffA);
;             PG8_WAIT_V(8); PG8_WAIT_L(0); PG8_BAR; PG8_MMA(1, 0, At, B0); PG8_MMA(1, 1, At, B1); PG8_BAR; PG8_SCHED;
	s_add_i32 s34, 0, 0x18000
	s_add_i32 s35, 0, 0x1c000
	v_add_u32_e32 v78, s34, v163
	v_add_u32_e32 v170, s35, v163
	ds_read_b128 v[58:61], v78
	ds_read_b128 v[62:65], v78 offset:1024
	ds_read_b128 v[70:73], v78 offset:2048
	ds_read_b128 v[78:81], v78 offset:3072
	ds_read_b128 v[152:155], v170
	ds_read_b128 v[156:159], v170 offset:1024
	ds_read_b128 v[166:169], v170 offset:2048
	ds_read_b128 v[170:173], v170 offset:3072
	s_add_u32 s6, s60, 0x100000
	s_addc_u32 s7, s61, 0
	s_mov_b32 m0, s77
	ds_read_b128 v[174:177], v165 offset:32768
	ds_read_b128 v[178:181], v165 offset:33792
	ds_read_b128 v[182:185], v165 offset:34816
	ds_read_b128 v[186:189], v165 offset:35840
	ds_read_b128 v[190:193], v165 offset:36864
	ds_read_b128 v[194:197], v165 offset:37888
	ds_read_b128 v[198:201], v165 offset:38912
	ds_read_b128 v[202:205], v165 offset:39936
	global_load_lds_dwordx4 v0, s[6:7]
	s_mov_b32 m0, s82
	s_nop 0
	global_load_lds_dwordx4 v146, s[6:7]
	s_waitcnt vmcnt(8) lgkmcnt(0)
	s_barrier
	s_setprio 1
	v_mfma_f32_16x16x32_bf16 v[142:145], v[58:61], v[174:177], v[142:145]
	v_mfma_f32_16x16x32_bf16 v[138:141], v[70:73], v[174:177], v[138:141]
	v_mfma_f32_16x16x32_bf16 v[126:129], v[58:61], v[182:185], v[126:129]
	v_mfma_f32_16x16x32_bf16 v[122:125], v[70:73], v[182:185], v[122:125]
	v_mfma_f32_16x16x32_bf16 v[110:113], v[58:61], v[190:193], v[110:113]
	v_mfma_f32_16x16x32_bf16 v[106:109], v[70:73], v[190:193], v[106:109]
	v_mfma_f32_16x16x32_bf16 v[94:97], v[58:61], v[198:201], v[94:97]
	v_mfma_f32_16x16x32_bf16 v[90:93], v[70:73], v[198:201], v[90:93]
	v_mfma_f32_16x16x32_bf16 v[142:145], v[62:65], v[178:181], v[142:145]
	v_mfma_f32_16x16x32_bf16 v[138:141], v[78:81], v[178:181], v[138:141]
	v_mfma_f32_16x16x32_bf16 v[126:129], v[62:65], v[186:189], v[126:129]
	v_mfma_f32_16x16x32_bf16 v[122:125], v[78:81], v[186:189], v[122:125]
	v_mfma_f32_16x16x32_bf16 v[110:113], v[62:65], v[194:197], v[110:113]
	v_mfma_f32_16x16x32_bf16 v[106:109], v[78:81], v[194:197], v[106:109]
	v_mfma_f32_16x16x32_bf16 v[94:97], v[62:65], v[202:205], v[94:97]
	v_mfma_f32_16x16x32_bf16 v[90:93], v[78:81], v[202:205], v[90:93]
	v_mfma_f32_16x16x32_bf16 v[134:137], v[152:155], v[174:177], v[134:137]
	v_mfma_f32_16x16x32_bf16 v[130:133], v[166:169], v[174:177], v[130:133]
	v_mfma_f32_16x16x32_bf16 v[118:121], v[152:155], v[182:185], v[118:121]
	v_mfma_f32_16x16x32_bf16 v[114:117], v[166:169], v[182:185], v[114:117]
	v_mfma_f32_16x16x32_bf16 v[102:105], v[152:155], v[190:193], v[102:105]
	v_mfma_f32_16x16x32_bf16 v[98:101], v[166:169], v[190:193], v[98:101]
	v_mfma_f32_16x16x32_bf16 v[86:89], v[152:155], v[198:201], v[86:89]
	v_mfma_f32_16x16x32_bf16 v[82:85], v[166:169], v[198:201], v[82:85]
	v_mfma_f32_16x16x32_bf16 v[134:137], v[156:159], v[178:181], v[134:137]
	v_mfma_f32_16x16x32_bf16 v[130:133], v[170:173], v[178:181], v[130:133]
	v_mfma_f32_16x16x32_bf16 v[118:121], v[156:159], v[186:189], v[118:121]
	v_mfma_f32_16x16x32_bf16 v[114:117], v[170:173], v[186:189], v[114:117]
	v_mfma_f32_16x16x32_bf16 v[102:105], v[156:159], v[194:197], v[102:105]
	v_mfma_f32_16x16x32_bf16 v[98:101], v[170:173], v[194:197], v[98:101]
	v_mfma_f32_16x16x32_bf16 v[86:89], v[156:159], v[202:205], v[86:89]
	v_mfma_f32_16x16x32_bf16 v[82:85], v[170:173], v[202:205], v[82:85]
	s_setprio 0
	s_barrier
	s_add_i32 s6, s34, s67
	s_mov_b32 m0, s6
	ds_read_b128 v[174:177], v165 offset:49152
	ds_read_b128 v[178:181], v165 offset:50176
	ds_read_b128 v[182:185], v165 offset:51200
	ds_read_b128 v[186:189], v165 offset:52224
	ds_read_b128 v[190:193], v165 offset:53248
	ds_read_b128 v[194:197], v165 offset:54272
	ds_read_b128 v[198:201], v165 offset:55296
	ds_read_b128 v[202:205], v165 offset:56320
	global_load_lds_dwordx4 v0, s[98:99]
	s_add_i32 m0, s6, 0x2000
	s_add_u32 s6, s58, 0x100080
	s_addc_u32 s7, s59, 0
	s_add_i32 s34, s35, s67
	global_load_lds_dwordx4 v146, s[98:99]
	s_mov_b32 m0, s34
	s_nop 0
	global_load_lds_dwordx4 v0, s[6:7]
	s_add_i32 m0, s34, 0x2000
	s_nop 0
	global_load_lds_dwordx4 v146, s[6:7]
	s_mov_b32 m0, s87
	s_nop 0
	global_load_lds_dwordx4 v0, s[100:101]
	s_mov_b32 m0, s92
	s_nop 0
	global_load_lds_dwordx4 v146, s[100:101]
	s_waitcnt vmcnt(8) lgkmcnt(0)
	s_barrier
	s_setprio 1
	v_mfma_f32_16x16x32_bf16 v[74:77], v[58:61], v[174:177], v[74:77]
	v_mfma_f32_16x16x32_bf16 v[66:69], v[70:73], v[174:177], v[66:69]
	v_mfma_f32_16x16x32_bf16 v[46:49], v[58:61], v[182:185], v[46:49]
	v_mfma_f32_16x16x32_bf16 v[42:45], v[70:73], v[182:185], v[42:45]
	v_mfma_f32_16x16x32_bf16 v[30:33], v[58:61], v[190:193], v[30:33]
	v_mfma_f32_16x16x32_bf16 v[26:29], v[70:73], v[190:193], v[26:29]
	v_mfma_f32_16x16x32_bf16 v[14:17], v[58:61], v[198:201], v[14:17]
	v_mfma_f32_16x16x32_bf16 v[10:13], v[70:73], v[198:201], v[10:13]
	v_mfma_f32_16x16x32_bf16 v[74:77], v[62:65], v[178:181], v[74:77]
	v_mfma_f32_16x16x32_bf16 v[66:69], v[78:81], v[178:181], v[66:69]
	v_mfma_f32_16x16x32_bf16 v[46:49], v[62:65], v[186:189], v[46:49]
	v_mfma_f32_16x16x32_bf16 v[42:45], v[78:81], v[186:189], v[42:45]
	v_mfma_f32_16x16x32_bf16 v[30:33], v[62:65], v[194:197], v[30:33]
	v_mfma_f32_16x16x32_bf16 v[26:29], v[78:81], v[194:197], v[26:29]
	v_mfma_f32_16x16x32_bf16 v[14:17], v[62:65], v[202:205], v[14:17]
	v_mfma_f32_16x16x32_bf16 v[10:13], v[78:81], v[202:205], v[10:13]
	v_mfma_f32_16x16x32_bf16 v[54:57], v[152:155], v[174:177], v[54:57]
	v_mfma_f32_16x16x32_bf16 v[50:53], v[166:169], v[174:177], v[50:53]
	v_mfma_f32_16x16x32_bf16 v[38:41], v[152:155], v[182:185], v[38:41]
	v_mfma_f32_16x16x32_bf16 v[34:37], v[166:169], v[182:185], v[34:37]
	v_mfma_f32_16x16x32_bf16 v[22:25], v[152:155], v[190:193], v[22:25]
	v_mfma_f32_16x16x32_bf16 v[18:21], v[166:169], v[190:193], v[18:21]
	v_mfma_f32_16x16x32_bf16 v[6:9], v[152:155], v[198:201], v[6:9]
	v_mfma_f32_16x16x32_bf16 v[2:5], v[166:169], v[198:201], v[2:5]
	v_mfma_f32_16x16x32_bf16 v[58:61], v[156:159], v[178:181], v[54:57]
	v_mfma_f32_16x16x32_bf16 v[50:53], v[170:173], v[178:181], v[50:53]
	v_mfma_f32_16x16x32_bf16 v[38:41], v[156:159], v[186:189], v[38:41]
	v_mfma_f32_16x16x32_bf16 v[34:37], v[170:173], v[186:189], v[34:37]
	v_mfma_f32_16x16x32_bf16 v[22:25], v[156:159], v[194:197], v[22:25]
	v_mfma_f32_16x16x32_bf16 v[18:21], v[170:173], v[194:197], v[18:21]
	v_mfma_f32_16x16x32_bf16 v[6:9], v[156:159], v[202:205], v[6:9]
	v_mfma_f32_16x16x32_bf16 v[2:5], v[170:173], v[202:205], v[2:5]
	s_setprio 0
	s_barrier
	s_add_u32 s25, s25, 0x100
	s_addc_u32 s27, s27, 0
	s_cmp_ge_i32 s51, s4
	s_mov_b64 s[34:35], s[40:41]
	s_mov_b32 s49, s51
	s_cbranch_scc0 .LBB0_1122
	s_and_b64 vcc, exec, s[46:47]
	s_cbranch_vccz .LBB0_1125
